# GEMM K-loop load segments: LDS-DMA issues interleaved with the ds_read fragments instead of all DMAs first
# baseline (speedup 1.0000x reference)
.LBB0_217:
	s_add_u32 s36, s34, 0xfffc0080
	s_addc_u32 s37, s35, -1
	s_cmp_eq_u32 s71, 12
	s_cselect_b32 s39, s7, s37
	s_cselect_b32 s38, s25, s36
	s_cselect_b32 s37, s23, s70
	s_cselect_b32 s36, s68, s69
	v_lshl_add_u64 v[150:151], s[34:35], 0, v[138:139]
	s_add_i32 m0, s31, 0xc000
	s_nop 0
	global_load_lds_dwordx4 v[150:151], off
	ds_read_b128 v[146:149], v155
	ds_read_b128 v[158:161], v155 offset:1024
	ds_read_b128 v[162:165], v155 offset:2048
	ds_read_b128 v[166:169], v155 offset:3072
	ds_read_b128 v[170:173], v156
	ds_read_b128 v[174:177], v156 offset:1024
	ds_read_b128 v[178:181], v156 offset:2048
	ds_read_b128 v[182:185], v156 offset:3072
	v_lshl_add_u64 v[150:151], s[34:35], 0, v[140:141]
	s_add_i32 m0, s31, 0xe000
	s_nop 0
	global_load_lds_dwordx4 v[150:151], off
	ds_read_b128 v[186:189], v157
	ds_read_b128 v[190:193], v157 offset:1024
	ds_read_b128 v[194:197], v157 offset:2048
	ds_read_b128 v[198:201], v157 offset:3072
	ds_read_b128 v[202:205], v157 offset:4096
	ds_read_b128 v[206:209], v157 offset:5120
	ds_read_b128 v[210:213], v157 offset:6144
	ds_read_b128 v[214:217], v157 offset:7168
	s_waitcnt vmcnt(8)
	s_waitcnt lgkmcnt(0)
	s_setprio 1
	s_barrier
	v_mfma_f32_16x16x32_bf16 v[124:127], v[146:149], v[186:189], v[124:127]
	v_mfma_f32_16x16x32_bf16 v[120:123], v[162:165], v[186:189], v[120:123]
	v_mfma_f32_16x16x32_bf16 v[108:111], v[146:149], v[194:197], v[108:111]
	v_mfma_f32_16x16x32_bf16 v[104:107], v[162:165], v[194:197], v[104:107]
	v_mfma_f32_16x16x32_bf16 v[92:95], v[146:149], v[202:205], v[92:95]
	v_mfma_f32_16x16x32_bf16 v[88:91], v[162:165], v[202:205], v[88:91]
	v_mfma_f32_16x16x32_bf16 v[76:79], v[146:149], v[210:213], v[76:79]
	v_mfma_f32_16x16x32_bf16 v[72:75], v[162:165], v[210:213], v[72:75]
	v_mfma_f32_16x16x32_bf16 v[124:127], v[158:161], v[190:193], v[124:127]
	v_mfma_f32_16x16x32_bf16 v[120:123], v[166:169], v[190:193], v[120:123]
	v_mfma_f32_16x16x32_bf16 v[108:111], v[158:161], v[198:201], v[108:111]
	v_mfma_f32_16x16x32_bf16 v[104:107], v[166:169], v[198:201], v[104:107]
	v_mfma_f32_16x16x32_bf16 v[92:95], v[158:161], v[206:209], v[92:95]
	v_mfma_f32_16x16x32_bf16 v[88:91], v[166:169], v[206:209], v[88:91]
	v_mfma_f32_16x16x32_bf16 v[76:79], v[158:161], v[214:217], v[76:79]
	v_mfma_f32_16x16x32_bf16 v[72:75], v[166:169], v[214:217], v[72:75]
	s_setprio 0
	s_setprio 1
	v_mfma_f32_16x16x32_bf16 v[116:119], v[170:173], v[186:189], v[116:119]
	v_mfma_f32_16x16x32_bf16 v[112:115], v[178:181], v[186:189], v[112:115]
	v_mfma_f32_16x16x32_bf16 v[100:103], v[170:173], v[194:197], v[100:103]
	v_mfma_f32_16x16x32_bf16 v[96:99], v[178:181], v[194:197], v[96:99]
	v_mfma_f32_16x16x32_bf16 v[84:87], v[170:173], v[202:205], v[84:87]
	v_mfma_f32_16x16x32_bf16 v[80:83], v[178:181], v[202:205], v[80:83]
	v_mfma_f32_16x16x32_bf16 v[68:71], v[170:173], v[210:213], v[68:71]
	v_mfma_f32_16x16x32_bf16 v[64:67], v[178:181], v[210:213], v[64:67]
	v_mfma_f32_16x16x32_bf16 v[116:119], v[174:177], v[190:193], v[116:119]
	v_mfma_f32_16x16x32_bf16 v[112:115], v[182:185], v[190:193], v[112:115]
	v_mfma_f32_16x16x32_bf16 v[100:103], v[174:177], v[198:201], v[100:103]
	v_mfma_f32_16x16x32_bf16 v[96:99], v[182:185], v[198:201], v[96:99]
	v_mfma_f32_16x16x32_bf16 v[84:87], v[174:177], v[206:209], v[84:87]
	v_mfma_f32_16x16x32_bf16 v[80:83], v[182:185], v[206:209], v[80:83]
	v_mfma_f32_16x16x32_bf16 v[68:71], v[174:177], v[214:217], v[68:71]
	v_mfma_f32_16x16x32_bf16 v[64:67], v[182:185], v[214:217], v[64:67]
	s_barrier
	s_setprio 0
	s_add_i32 s72, s65, s43
	v_lshl_add_u64 v[150:151], s[36:37], 0, v[130:131]
	s_mov_b32 m0, s72
	s_nop 0
	global_load_lds_dwordx4 v[150:151], off
	ds_read_b128 v[186:189], v157 offset:16384
	ds_read_b128 v[190:193], v157 offset:17408
	s_add_i32 m0, s72, 0x2000
	s_add_u32 s72, s36, 0x40000
	v_lshl_add_u64 v[218:219], s[36:37], 0, v[134:135]
	s_addc_u32 s73, s37, 0
	s_add_i32 s74, s67, s43
	global_load_lds_dwordx4 v[218:219], off
	ds_read_b128 v[194:197], v157 offset:18432
	ds_read_b128 v[198:201], v157 offset:19456
	v_lshl_add_u64 v[220:221], s[72:73], 0, v[130:131]
	s_mov_b32 m0, s74
	v_lshl_add_u64 v[222:223], s[38:39], 0, v[132:133]
	global_load_lds_dwordx4 v[220:221], off
	ds_read_b128 v[202:205], v157 offset:20480
	ds_read_b128 v[206:209], v157 offset:21504
	v_lshl_add_u64 v[220:221], s[72:73], 0, v[134:135]
	s_add_i32 m0, s74, 0x2000
	s_nop 0
	global_load_lds_dwordx4 v[220:221], off
	ds_read_b128 v[210:213], v157 offset:22528
	ds_read_b128 v[214:217], v157 offset:23552
	v_lshl_add_u64 v[220:221], s[38:39], 0, v[128:129]
	s_mov_b32 m0, s31
	s_nop 0
	global_load_lds_dwordx4 v[220:221], off
	s_mov_b32 m0, s46
	s_nop 0
	global_load_lds_dwordx4 v[222:223], off
	s_waitcnt vmcnt(8)
	s_waitcnt lgkmcnt(0)
	s_setprio 1
	s_barrier
	v_mfma_f32_16x16x32_bf16 v[60:63], v[146:149], v[186:189], v[60:63]
	v_mfma_f32_16x16x32_bf16 v[56:59], v[162:165], v[186:189], v[56:59]
	v_mfma_f32_16x16x32_bf16 v[44:47], v[146:149], v[194:197], v[44:47]
	v_mfma_f32_16x16x32_bf16 v[40:43], v[162:165], v[194:197], v[40:43]
	v_mfma_f32_16x16x32_bf16 v[28:31], v[146:149], v[202:205], v[28:31]
	v_mfma_f32_16x16x32_bf16 v[24:27], v[162:165], v[202:205], v[24:27]
	v_mfma_f32_16x16x32_bf16 v[12:15], v[146:149], v[210:213], v[12:15]
	v_mfma_f32_16x16x32_bf16 v[8:11], v[162:165], v[210:213], v[8:11]
	v_mfma_f32_16x16x32_bf16 v[60:63], v[158:161], v[190:193], v[60:63]
	v_mfma_f32_16x16x32_bf16 v[56:59], v[166:169], v[190:193], v[56:59]
	v_mfma_f32_16x16x32_bf16 v[44:47], v[158:161], v[198:201], v[44:47]
	v_mfma_f32_16x16x32_bf16 v[40:43], v[166:169], v[198:201], v[40:43]
	v_mfma_f32_16x16x32_bf16 v[28:31], v[158:161], v[206:209], v[28:31]
	v_mfma_f32_16x16x32_bf16 v[24:27], v[166:169], v[206:209], v[24:27]
	v_mfma_f32_16x16x32_bf16 v[12:15], v[158:161], v[214:217], v[12:15]
	v_mfma_f32_16x16x32_bf16 v[8:11], v[166:169], v[214:217], v[8:11]
	s_setprio 0
	s_setprio 1
	v_mfma_f32_16x16x32_bf16 v[52:55], v[170:173], v[186:189], v[52:55]
	v_mfma_f32_16x16x32_bf16 v[48:51], v[178:181], v[186:189], v[48:51]
	v_mfma_f32_16x16x32_bf16 v[36:39], v[170:173], v[194:197], v[36:39]
	v_mfma_f32_16x16x32_bf16 v[32:35], v[178:181], v[194:197], v[32:35]
	v_mfma_f32_16x16x32_bf16 v[20:23], v[170:173], v[202:205], v[20:23]
	v_mfma_f32_16x16x32_bf16 v[16:19], v[178:181], v[202:205], v[16:19]
	v_mfma_f32_16x16x32_bf16 v[4:7], v[170:173], v[210:213], v[4:7]
	v_mfma_f32_16x16x32_bf16 v[0:3], v[178:181], v[210:213], v[0:3]
	v_mfma_f32_16x16x32_bf16 v[52:55], v[174:177], v[190:193], v[52:55]
	v_mfma_f32_16x16x32_bf16 v[48:51], v[182:185], v[190:193], v[48:51]
	v_mfma_f32_16x16x32_bf16 v[36:39], v[174:177], v[198:201], v[36:39]
	v_mfma_f32_16x16x32_bf16 v[32:35], v[182:185], v[198:201], v[32:35]
	v_mfma_f32_16x16x32_bf16 v[20:23], v[174:177], v[206:209], v[20:23]
	v_mfma_f32_16x16x32_bf16 v[16:19], v[182:185], v[206:209], v[16:19]
	v_mfma_f32_16x16x32_bf16 v[4:7], v[174:177], v[214:217], v[4:7]
	v_mfma_f32_16x16x32_bf16 v[0:3], v[182:185], v[214:217], v[0:3]
	s_barrier
	s_setprio 0
	s_add_i32 s72, 0, 0x18000
	s_add_i32 s73, 0, 0x1c000
	s_add_u32 s38, s38, 0x40000
	s_addc_u32 s39, s39, 0
	s_mov_b32 m0, s47
	v_lshl_add_u64 v[224:225], s[38:39], 0, v[128:129]
	global_load_lds_dwordx4 v[224:225], off
	v_add_u32_e32 v136, s72, v153
	ds_read_b128 v[146:149], v136
	ds_read_b128 v[158:161], v136 offset:1024
	ds_read_b128 v[162:165], v136 offset:2048
	ds_read_b128 v[166:169], v136 offset:3072
	v_add_u32_e32 v136, s73, v153
	ds_read_b128 v[170:173], v136
	ds_read_b128 v[174:177], v136 offset:1024
	ds_read_b128 v[178:181], v136 offset:2048
	ds_read_b128 v[182:185], v136 offset:3072
	v_lshl_add_u64 v[224:225], s[38:39], 0, v[132:133]
	s_mov_b32 m0, s48
	s_nop 0
	global_load_lds_dwordx4 v[224:225], off
	ds_read_b128 v[186:189], v157 offset:32768
	ds_read_b128 v[190:193], v157 offset:33792
	ds_read_b128 v[194:197], v157 offset:34816
	ds_read_b128 v[198:201], v157 offset:35840
	ds_read_b128 v[202:205], v157 offset:36864
	ds_read_b128 v[206:209], v157 offset:37888
	ds_read_b128 v[210:213], v157 offset:38912
	ds_read_b128 v[214:217], v157 offset:39936
	s_waitcnt vmcnt(8)
	s_waitcnt lgkmcnt(0)
	s_setprio 1
	s_barrier
	v_mfma_f32_16x16x32_bf16 v[124:127], v[146:149], v[186:189], v[124:127]
	v_mfma_f32_16x16x32_bf16 v[120:123], v[162:165], v[186:189], v[120:123]
	v_mfma_f32_16x16x32_bf16 v[108:111], v[146:149], v[194:197], v[108:111]
	v_mfma_f32_16x16x32_bf16 v[104:107], v[162:165], v[194:197], v[104:107]
	v_mfma_f32_16x16x32_bf16 v[92:95], v[146:149], v[202:205], v[92:95]
	v_mfma_f32_16x16x32_bf16 v[88:91], v[162:165], v[202:205], v[88:91]
	v_mfma_f32_16x16x32_bf16 v[76:79], v[146:149], v[210:213], v[76:79]
	v_mfma_f32_16x16x32_bf16 v[72:75], v[162:165], v[210:213], v[72:75]
	v_mfma_f32_16x16x32_bf16 v[124:127], v[158:161], v[190:193], v[124:127]
	v_mfma_f32_16x16x32_bf16 v[120:123], v[166:169], v[190:193], v[120:123]
	v_mfma_f32_16x16x32_bf16 v[108:111], v[158:161], v[198:201], v[108:111]
	v_mfma_f32_16x16x32_bf16 v[104:107], v[166:169], v[198:201], v[104:107]
	v_mfma_f32_16x16x32_bf16 v[92:95], v[158:161], v[206:209], v[92:95]
	v_mfma_f32_16x16x32_bf16 v[88:91], v[166:169], v[206:209], v[88:91]
	v_mfma_f32_16x16x32_bf16 v[76:79], v[158:161], v[214:217], v[76:79]
	v_mfma_f32_16x16x32_bf16 v[72:75], v[166:169], v[214:217], v[72:75]
	s_setprio 0
	s_setprio 1
	v_mfma_f32_16x16x32_bf16 v[116:119], v[170:173], v[186:189], v[116:119]
	v_mfma_f32_16x16x32_bf16 v[112:115], v[178:181], v[186:189], v[112:115]
	v_mfma_f32_16x16x32_bf16 v[100:103], v[170:173], v[194:197], v[100:103]
	v_mfma_f32_16x16x32_bf16 v[96:99], v[178:181], v[194:197], v[96:99]
	v_mfma_f32_16x16x32_bf16 v[84:87], v[170:173], v[202:205], v[84:87]
	v_mfma_f32_16x16x32_bf16 v[80:83], v[178:181], v[202:205], v[80:83]
	v_mfma_f32_16x16x32_bf16 v[68:71], v[170:173], v[210:213], v[68:71]
	v_mfma_f32_16x16x32_bf16 v[64:67], v[178:181], v[210:213], v[64:67]
	v_mfma_f32_16x16x32_bf16 v[116:119], v[174:177], v[190:193], v[116:119]
	v_mfma_f32_16x16x32_bf16 v[112:115], v[182:185], v[190:193], v[112:115]
	v_mfma_f32_16x16x32_bf16 v[100:103], v[174:177], v[198:201], v[100:103]
	v_mfma_f32_16x16x32_bf16 v[96:99], v[182:185], v[198:201], v[96:99]
	v_mfma_f32_16x16x32_bf16 v[84:87], v[174:177], v[206:209], v[84:87]
	v_mfma_f32_16x16x32_bf16 v[80:83], v[182:185], v[206:209], v[80:83]
	v_mfma_f32_16x16x32_bf16 v[68:71], v[174:177], v[214:217], v[68:71]
	v_mfma_f32_16x16x32_bf16 v[64:67], v[182:185], v[214:217], v[64:67]
	s_barrier
	s_setprio 0
	s_add_i32 s38, s72, s43
	v_lshl_add_u64 v[150:151], v[150:151], 0, s[12:13]
	s_mov_b32 m0, s38
	s_nop 0
	global_load_lds_dwordx4 v[150:151], off
	ds_read_b128 v[186:189], v157 offset:49152
	ds_read_b128 v[190:193], v157 offset:50176
	s_add_i32 m0, s38, 0x2000
	s_add_u32 s36, s36, 0x40080
	v_lshl_add_u64 v[150:151], v[218:219], 0, s[12:13]
	s_addc_u32 s37, s37, 0
	s_add_i32 s38, s73, s43
	global_load_lds_dwordx4 v[150:151], off
	ds_read_b128 v[194:197], v157 offset:51200
	ds_read_b128 v[198:201], v157 offset:52224
	v_lshl_add_u64 v[150:151], s[36:37], 0, v[130:131]
	s_mov_b32 m0, s38
	s_nop 0
	global_load_lds_dwordx4 v[150:151], off
	ds_read_b128 v[202:205], v157 offset:53248
	ds_read_b128 v[206:209], v157 offset:54272
	v_lshl_add_u64 v[150:151], s[36:37], 0, v[134:135]
	s_add_i32 m0, s38, 0x2000
	s_nop 0
	global_load_lds_dwordx4 v[150:151], off
	ds_read_b128 v[210:213], v157 offset:55296
	ds_read_b128 v[214:217], v157 offset:56320
	v_lshl_add_u64 v[150:151], v[220:221], 0, s[12:13]
	s_mov_b32 m0, s60
	s_nop 0
	global_load_lds_dwordx4 v[150:151], off
	v_lshl_add_u64 v[150:151], v[222:223], 0, s[12:13]
	s_mov_b32 m0, s61
	s_nop 0
	global_load_lds_dwordx4 v[150:151], off
	s_waitcnt vmcnt(8)
	s_waitcnt lgkmcnt(0)
	s_setprio 1
	s_barrier
	v_mfma_f32_16x16x32_bf16 v[60:63], v[146:149], v[186:189], v[60:63]
	v_mfma_f32_16x16x32_bf16 v[56:59], v[162:165], v[186:189], v[56:59]
	v_mfma_f32_16x16x32_bf16 v[44:47], v[146:149], v[194:197], v[44:47]
	v_mfma_f32_16x16x32_bf16 v[40:43], v[162:165], v[194:197], v[40:43]
	v_mfma_f32_16x16x32_bf16 v[28:31], v[146:149], v[202:205], v[28:31]
	v_mfma_f32_16x16x32_bf16 v[24:27], v[162:165], v[202:205], v[24:27]
	v_mfma_f32_16x16x32_bf16 v[12:15], v[146:149], v[210:213], v[12:15]
	v_mfma_f32_16x16x32_bf16 v[8:11], v[162:165], v[210:213], v[8:11]
	v_mfma_f32_16x16x32_bf16 v[60:63], v[158:161], v[190:193], v[60:63]
	v_mfma_f32_16x16x32_bf16 v[56:59], v[166:169], v[190:193], v[56:59]
	v_mfma_f32_16x16x32_bf16 v[44:47], v[158:161], v[198:201], v[44:47]
	v_mfma_f32_16x16x32_bf16 v[40:43], v[166:169], v[198:201], v[40:43]
	v_mfma_f32_16x16x32_bf16 v[28:31], v[158:161], v[206:209], v[28:31]
	v_mfma_f32_16x16x32_bf16 v[24:27], v[166:169], v[206:209], v[24:27]
	v_mfma_f32_16x16x32_bf16 v[12:15], v[158:161], v[214:217], v[12:15]
	v_mfma_f32_16x16x32_bf16 v[8:11], v[166:169], v[214:217], v[8:11]
	s_setprio 0
	s_setprio 1
	v_mfma_f32_16x16x32_bf16 v[52:55], v[170:173], v[186:189], v[52:55]
	v_mfma_f32_16x16x32_bf16 v[48:51], v[178:181], v[186:189], v[48:51]
	v_mfma_f32_16x16x32_bf16 v[36:39], v[170:173], v[194:197], v[36:39]
	v_mfma_f32_16x16x32_bf16 v[32:35], v[178:181], v[194:197], v[32:35]
	v_mfma_f32_16x16x32_bf16 v[20:23], v[170:173], v[202:205], v[20:23]
	v_mfma_f32_16x16x32_bf16 v[16:19], v[178:181], v[202:205], v[16:19]
	v_mfma_f32_16x16x32_bf16 v[4:7], v[170:173], v[210:213], v[4:7]
	v_mfma_f32_16x16x32_bf16 v[0:3], v[178:181], v[210:213], v[0:3]
	v_mfma_f32_16x16x32_bf16 v[52:55], v[174:177], v[190:193], v[52:55]
	v_mfma_f32_16x16x32_bf16 v[48:51], v[182:185], v[190:193], v[48:51]
	v_mfma_f32_16x16x32_bf16 v[36:39], v[174:177], v[198:201], v[36:39]
	v_mfma_f32_16x16x32_bf16 v[32:35], v[182:185], v[198:201], v[32:35]
	v_mfma_f32_16x16x32_bf16 v[20:23], v[174:177], v[206:209], v[20:23]
	v_mfma_f32_16x16x32_bf16 v[16:19], v[182:185], v[206:209], v[16:19]
	v_mfma_f32_16x16x32_bf16 v[4:7], v[174:177], v[214:217], v[4:7]
	v_mfma_f32_16x16x32_bf16 v[0:3], v[182:185], v[214:217], v[0:3]
	s_barrier
	s_setprio 0
	s_add_i32 s71, s71, 2
	s_add_u32 s34, s34, 0x100
	s_addc_u32 s35, s35, 0
	s_add_u32 s69, s69, 0x100
	s_addc_u32 s70, s70, 0
	s_cmp_gt_u32 s71, 13
	s_cbranch_scc0 .LBB0_217
	s_and_b64 vcc, exec, s[14:15]
	s_cbranch_vccz .LBB0_220
	s_barrier

.LBB0_471:
	s_add_u32 s34, s30, 0xfffc0080
	s_addc_u32 s35, s31, -1
	s_cmp_eq_u32 s69, 12
	s_cselect_b32 s37, s21, s35
	s_cselect_b32 s36, s27, s34
	s_cselect_b32 s35, s19, s68
	s_cselect_b32 s34, s64, s65
	v_lshl_add_u64 v[214:215], s[30:31], 0, v[184:185]
	s_add_i32 m0, s29, 0xc000
	s_nop 0
	global_load_lds_dwordx4 v[214:215], off
	ds_read_b128 v[128:131], v207
	ds_read_b128 v[132:135], v207 offset:1024
	ds_read_b128 v[136:139], v207 offset:2048
	ds_read_b128 v[140:143], v207 offset:3072
	ds_read_b128 v[144:147], v208
	ds_read_b128 v[148:151], v208 offset:1024
	ds_read_b128 v[152:155], v208 offset:2048
	ds_read_b128 v[156:159], v208 offset:3072
	v_lshl_add_u64 v[214:215], s[30:31], 0, v[186:187]
	s_add_i32 m0, s29, 0xe000
	s_nop 0
	global_load_lds_dwordx4 v[214:215], off
	ds_read_b128 v[160:163], v209
	ds_read_b128 v[164:167], v209 offset:1024
	ds_read_b128 v[168:171], v209 offset:2048
	ds_read_b128 v[172:175], v209 offset:3072
	ds_read_b128 v[192:195], v209 offset:4096
	ds_read_b128 v[196:199], v209 offset:5120
	ds_read_b128 v[200:203], v209 offset:6144
	ds_read_b128 v[210:213], v209 offset:7168
	s_waitcnt vmcnt(8)
	s_waitcnt lgkmcnt(0)
	s_setprio 1
	s_barrier
	v_mfma_f32_16x16x32_bf16 v[124:127], v[128:131], v[160:163], v[124:127]
	v_mfma_f32_16x16x32_bf16 v[120:123], v[136:139], v[160:163], v[120:123]
	v_mfma_f32_16x16x32_bf16 v[108:111], v[128:131], v[168:171], v[108:111]
	v_mfma_f32_16x16x32_bf16 v[104:107], v[136:139], v[168:171], v[104:107]
	v_mfma_f32_16x16x32_bf16 v[92:95], v[128:131], v[192:195], v[92:95]
	v_mfma_f32_16x16x32_bf16 v[88:91], v[136:139], v[192:195], v[88:91]
	v_mfma_f32_16x16x32_bf16 v[76:79], v[128:131], v[200:203], v[76:79]
	v_mfma_f32_16x16x32_bf16 v[72:75], v[136:139], v[200:203], v[72:75]
	v_mfma_f32_16x16x32_bf16 v[124:127], v[132:135], v[164:167], v[124:127]
	v_mfma_f32_16x16x32_bf16 v[120:123], v[140:143], v[164:167], v[120:123]
	v_mfma_f32_16x16x32_bf16 v[108:111], v[132:135], v[172:175], v[108:111]
	v_mfma_f32_16x16x32_bf16 v[104:107], v[140:143], v[172:175], v[104:107]
	v_mfma_f32_16x16x32_bf16 v[92:95], v[132:135], v[196:199], v[92:95]
	v_mfma_f32_16x16x32_bf16 v[88:91], v[140:143], v[196:199], v[88:91]
	v_mfma_f32_16x16x32_bf16 v[76:79], v[132:135], v[210:213], v[76:79]
	v_mfma_f32_16x16x32_bf16 v[72:75], v[140:143], v[210:213], v[72:75]
	s_setprio 0
	s_setprio 1
	v_mfma_f32_16x16x32_bf16 v[116:119], v[144:147], v[160:163], v[116:119]
	v_mfma_f32_16x16x32_bf16 v[112:115], v[152:155], v[160:163], v[112:115]
	v_mfma_f32_16x16x32_bf16 v[100:103], v[144:147], v[168:171], v[100:103]
	v_mfma_f32_16x16x32_bf16 v[96:99], v[152:155], v[168:171], v[96:99]
	v_mfma_f32_16x16x32_bf16 v[84:87], v[144:147], v[192:195], v[84:87]
	v_mfma_f32_16x16x32_bf16 v[80:83], v[152:155], v[192:195], v[80:83]
	v_mfma_f32_16x16x32_bf16 v[68:71], v[144:147], v[200:203], v[68:71]
	v_mfma_f32_16x16x32_bf16 v[64:67], v[152:155], v[200:203], v[64:67]
	v_mfma_f32_16x16x32_bf16 v[116:119], v[148:151], v[164:167], v[116:119]
	v_mfma_f32_16x16x32_bf16 v[112:115], v[156:159], v[164:167], v[112:115]
	v_mfma_f32_16x16x32_bf16 v[100:103], v[148:151], v[172:175], v[100:103]
	v_mfma_f32_16x16x32_bf16 v[96:99], v[156:159], v[172:175], v[96:99]
	v_mfma_f32_16x16x32_bf16 v[84:87], v[148:151], v[196:199], v[84:87]
	v_mfma_f32_16x16x32_bf16 v[80:83], v[156:159], v[196:199], v[80:83]
	v_mfma_f32_16x16x32_bf16 v[68:71], v[148:151], v[210:213], v[68:71]
	v_mfma_f32_16x16x32_bf16 v[64:67], v[156:159], v[210:213], v[64:67]
	s_barrier
	s_setprio 0
	s_add_i32 s70, s62, s40
	v_lshl_add_u64 v[214:215], s[34:35], 0, v[178:179]
	s_mov_b32 m0, s70
	s_nop 0
	global_load_lds_dwordx4 v[214:215], off
	ds_read_b128 v[160:163], v209 offset:16384
	ds_read_b128 v[164:167], v209 offset:17408
	s_add_i32 m0, s70, 0x2000
	s_add_u32 s70, s34, 0x40000
	v_lshl_add_u64 v[216:217], s[34:35], 0, v[182:183]
	s_addc_u32 s71, s35, 0
	s_add_i32 s72, s63, s40
	global_load_lds_dwordx4 v[216:217], off
	ds_read_b128 v[168:171], v209 offset:18432
	ds_read_b128 v[172:175], v209 offset:19456
	v_lshl_add_u64 v[218:219], s[70:71], 0, v[178:179]
	s_mov_b32 m0, s72
	v_lshl_add_u64 v[220:221], s[36:37], 0, v[180:181]
	global_load_lds_dwordx4 v[218:219], off
	ds_read_b128 v[192:195], v209 offset:20480
	ds_read_b128 v[196:199], v209 offset:21504
	v_lshl_add_u64 v[218:219], s[70:71], 0, v[182:183]
	s_add_i32 m0, s72, 0x2000
	s_nop 0
	global_load_lds_dwordx4 v[218:219], off
	ds_read_b128 v[200:203], v209 offset:22528
	ds_read_b128 v[210:213], v209 offset:23552
	v_lshl_add_u64 v[218:219], s[36:37], 0, v[176:177]
	s_mov_b32 m0, s29
	s_nop 0
	global_load_lds_dwordx4 v[218:219], off
	s_mov_b32 m0, s41
	s_nop 0
	global_load_lds_dwordx4 v[220:221], off
	s_waitcnt vmcnt(8)
	s_waitcnt lgkmcnt(0)
	s_setprio 1
	s_barrier
	v_mfma_f32_16x16x32_bf16 v[60:63], v[128:131], v[160:163], v[60:63]
	v_mfma_f32_16x16x32_bf16 v[56:59], v[136:139], v[160:163], v[56:59]
	v_mfma_f32_16x16x32_bf16 v[44:47], v[128:131], v[168:171], v[44:47]
	v_mfma_f32_16x16x32_bf16 v[40:43], v[136:139], v[168:171], v[40:43]
	v_mfma_f32_16x16x32_bf16 v[28:31], v[128:131], v[192:195], v[28:31]
	v_mfma_f32_16x16x32_bf16 v[24:27], v[136:139], v[192:195], v[24:27]
	v_mfma_f32_16x16x32_bf16 v[12:15], v[128:131], v[200:203], v[12:15]
	v_mfma_f32_16x16x32_bf16 v[8:11], v[136:139], v[200:203], v[8:11]
	v_mfma_f32_16x16x32_bf16 v[60:63], v[132:135], v[164:167], v[60:63]
	v_mfma_f32_16x16x32_bf16 v[56:59], v[140:143], v[164:167], v[56:59]
	v_mfma_f32_16x16x32_bf16 v[44:47], v[132:135], v[172:175], v[44:47]
	v_mfma_f32_16x16x32_bf16 v[40:43], v[140:143], v[172:175], v[40:43]
	v_mfma_f32_16x16x32_bf16 v[28:31], v[132:135], v[196:199], v[28:31]
	v_mfma_f32_16x16x32_bf16 v[24:27], v[140:143], v[196:199], v[24:27]
	v_mfma_f32_16x16x32_bf16 v[12:15], v[132:135], v[210:213], v[12:15]
	v_mfma_f32_16x16x32_bf16 v[8:11], v[140:143], v[210:213], v[8:11]
	s_setprio 0
	s_setprio 1
	v_mfma_f32_16x16x32_bf16 v[52:55], v[144:147], v[160:163], v[52:55]
	v_mfma_f32_16x16x32_bf16 v[48:51], v[152:155], v[160:163], v[48:51]
	v_mfma_f32_16x16x32_bf16 v[36:39], v[144:147], v[168:171], v[36:39]
	v_mfma_f32_16x16x32_bf16 v[32:35], v[152:155], v[168:171], v[32:35]
	v_mfma_f32_16x16x32_bf16 v[20:23], v[144:147], v[192:195], v[20:23]
	v_mfma_f32_16x16x32_bf16 v[16:19], v[152:155], v[192:195], v[16:19]
	v_mfma_f32_16x16x32_bf16 v[4:7], v[144:147], v[200:203], v[4:7]
	v_mfma_f32_16x16x32_bf16 v[0:3], v[152:155], v[200:203], v[0:3]
	v_mfma_f32_16x16x32_bf16 v[52:55], v[148:151], v[164:167], v[52:55]
	v_mfma_f32_16x16x32_bf16 v[48:51], v[156:159], v[164:167], v[48:51]
	v_mfma_f32_16x16x32_bf16 v[36:39], v[148:151], v[172:175], v[36:39]
	v_mfma_f32_16x16x32_bf16 v[32:35], v[156:159], v[172:175], v[32:35]
	v_mfma_f32_16x16x32_bf16 v[20:23], v[148:151], v[196:199], v[20:23]
	v_mfma_f32_16x16x32_bf16 v[16:19], v[156:159], v[196:199], v[16:19]
	v_mfma_f32_16x16x32_bf16 v[4:7], v[148:151], v[210:213], v[4:7]
	v_mfma_f32_16x16x32_bf16 v[0:3], v[156:159], v[210:213], v[0:3]
	s_barrier
	s_setprio 0
	s_add_i32 s70, 0, 0x18000
	s_add_i32 s71, 0, 0x1c000
	s_add_u32 s36, s36, 0x40000
	s_addc_u32 s37, s37, 0
	s_mov_b32 m0, s42
	v_lshl_add_u64 v[222:223], s[36:37], 0, v[176:177]
	global_load_lds_dwordx4 v[222:223], off
	v_add_u32_e32 v140, s70, v206
	v_add_u32_e32 v156, s71, v206
	ds_read_b128 v[128:131], v140
	ds_read_b128 v[132:135], v140 offset:1024
	ds_read_b128 v[136:139], v140 offset:2048
	ds_read_b128 v[140:143], v140 offset:3072
	ds_read_b128 v[144:147], v156
	ds_read_b128 v[148:151], v156 offset:1024
	ds_read_b128 v[152:155], v156 offset:2048
	ds_read_b128 v[156:159], v156 offset:3072
	v_lshl_add_u64 v[222:223], s[36:37], 0, v[180:181]
	s_mov_b32 m0, s43
	s_nop 0
	global_load_lds_dwordx4 v[222:223], off
	ds_read_b128 v[160:163], v209 offset:32768
	ds_read_b128 v[164:167], v209 offset:33792
	ds_read_b128 v[168:171], v209 offset:34816
	ds_read_b128 v[172:175], v209 offset:35840
	ds_read_b128 v[192:195], v209 offset:36864
	ds_read_b128 v[196:199], v209 offset:37888
	ds_read_b128 v[200:203], v209 offset:38912
	ds_read_b128 v[210:213], v209 offset:39936
	s_waitcnt vmcnt(8)
	s_waitcnt lgkmcnt(0)
	s_setprio 1
	s_barrier
	v_mfma_f32_16x16x32_bf16 v[124:127], v[128:131], v[160:163], v[124:127]
	v_mfma_f32_16x16x32_bf16 v[120:123], v[136:139], v[160:163], v[120:123]
	v_mfma_f32_16x16x32_bf16 v[108:111], v[128:131], v[168:171], v[108:111]
	v_mfma_f32_16x16x32_bf16 v[104:107], v[136:139], v[168:171], v[104:107]
	v_mfma_f32_16x16x32_bf16 v[92:95], v[128:131], v[192:195], v[92:95]
	v_mfma_f32_16x16x32_bf16 v[88:91], v[136:139], v[192:195], v[88:91]
	v_mfma_f32_16x16x32_bf16 v[76:79], v[128:131], v[200:203], v[76:79]
	v_mfma_f32_16x16x32_bf16 v[72:75], v[136:139], v[200:203], v[72:75]
	v_mfma_f32_16x16x32_bf16 v[124:127], v[132:135], v[164:167], v[124:127]
	v_mfma_f32_16x16x32_bf16 v[120:123], v[140:143], v[164:167], v[120:123]
	v_mfma_f32_16x16x32_bf16 v[108:111], v[132:135], v[172:175], v[108:111]
	v_mfma_f32_16x16x32_bf16 v[104:107], v[140:143], v[172:175], v[104:107]
	v_mfma_f32_16x16x32_bf16 v[92:95], v[132:135], v[196:199], v[92:95]
	v_mfma_f32_16x16x32_bf16 v[88:91], v[140:143], v[196:199], v[88:91]
	v_mfma_f32_16x16x32_bf16 v[76:79], v[132:135], v[210:213], v[76:79]
	v_mfma_f32_16x16x32_bf16 v[72:75], v[140:143], v[210:213], v[72:75]
	s_setprio 0
	s_setprio 1
	v_mfma_f32_16x16x32_bf16 v[116:119], v[144:147], v[160:163], v[116:119]
	v_mfma_f32_16x16x32_bf16 v[112:115], v[152:155], v[160:163], v[112:115]
	v_mfma_f32_16x16x32_bf16 v[100:103], v[144:147], v[168:171], v[100:103]
	v_mfma_f32_16x16x32_bf16 v[96:99], v[152:155], v[168:171], v[96:99]
	v_mfma_f32_16x16x32_bf16 v[84:87], v[144:147], v[192:195], v[84:87]
	v_mfma_f32_16x16x32_bf16 v[80:83], v[152:155], v[192:195], v[80:83]
	v_mfma_f32_16x16x32_bf16 v[68:71], v[144:147], v[200:203], v[68:71]
	v_mfma_f32_16x16x32_bf16 v[64:67], v[152:155], v[200:203], v[64:67]
	v_mfma_f32_16x16x32_bf16 v[116:119], v[148:151], v[164:167], v[116:119]
	v_mfma_f32_16x16x32_bf16 v[112:115], v[156:159], v[164:167], v[112:115]
	v_mfma_f32_16x16x32_bf16 v[100:103], v[148:151], v[172:175], v[100:103]
	v_mfma_f32_16x16x32_bf16 v[96:99], v[156:159], v[172:175], v[96:99]
	v_mfma_f32_16x16x32_bf16 v[84:87], v[148:151], v[196:199], v[84:87]
	v_mfma_f32_16x16x32_bf16 v[80:83], v[156:159], v[196:199], v[80:83]
	v_mfma_f32_16x16x32_bf16 v[68:71], v[148:151], v[210:213], v[68:71]
	v_mfma_f32_16x16x32_bf16 v[64:67], v[156:159], v[210:213], v[64:67]
	s_barrier
	s_setprio 0
	s_add_i32 s36, s70, s40
	v_lshl_add_u64 v[214:215], v[214:215], 0, s[14:15]
	s_mov_b32 m0, s36
	s_nop 0
	global_load_lds_dwordx4 v[214:215], off
	ds_read_b128 v[160:163], v209 offset:49152
	ds_read_b128 v[164:167], v209 offset:50176
	s_add_i32 m0, s36, 0x2000
	s_add_u32 s34, s34, 0x40080
	v_lshl_add_u64 v[214:215], v[216:217], 0, s[14:15]
	s_addc_u32 s35, s35, 0
	s_add_i32 s36, s71, s40
	global_load_lds_dwordx4 v[214:215], off
	ds_read_b128 v[168:171], v209 offset:51200
	ds_read_b128 v[172:175], v209 offset:52224
	v_lshl_add_u64 v[214:215], s[34:35], 0, v[178:179]
	s_mov_b32 m0, s36
	s_nop 0
	global_load_lds_dwordx4 v[214:215], off
	ds_read_b128 v[192:195], v209 offset:53248
	ds_read_b128 v[196:199], v209 offset:54272
	v_lshl_add_u64 v[214:215], s[34:35], 0, v[182:183]
	s_add_i32 m0, s36, 0x2000
	s_nop 0
	global_load_lds_dwordx4 v[214:215], off
	ds_read_b128 v[200:203], v209 offset:55296
	ds_read_b128 v[210:213], v209 offset:56320
	v_lshl_add_u64 v[214:215], v[218:219], 0, s[14:15]
	s_mov_b32 m0, s49
	s_nop 0
	global_load_lds_dwordx4 v[214:215], off
	v_lshl_add_u64 v[214:215], v[220:221], 0, s[14:15]
	s_mov_b32 m0, s50
	s_nop 0
	global_load_lds_dwordx4 v[214:215], off
	s_waitcnt vmcnt(8)
	s_waitcnt lgkmcnt(0)
	s_setprio 1
	s_barrier
	v_mfma_f32_16x16x32_bf16 v[60:63], v[128:131], v[160:163], v[60:63]
	v_mfma_f32_16x16x32_bf16 v[56:59], v[136:139], v[160:163], v[56:59]
	v_mfma_f32_16x16x32_bf16 v[44:47], v[128:131], v[168:171], v[44:47]
	v_mfma_f32_16x16x32_bf16 v[40:43], v[136:139], v[168:171], v[40:43]
	v_mfma_f32_16x16x32_bf16 v[28:31], v[128:131], v[192:195], v[28:31]
	v_mfma_f32_16x16x32_bf16 v[24:27], v[136:139], v[192:195], v[24:27]
	v_mfma_f32_16x16x32_bf16 v[12:15], v[128:131], v[200:203], v[12:15]
	v_mfma_f32_16x16x32_bf16 v[8:11], v[136:139], v[200:203], v[8:11]
	v_mfma_f32_16x16x32_bf16 v[60:63], v[132:135], v[164:167], v[60:63]
	v_mfma_f32_16x16x32_bf16 v[56:59], v[140:143], v[164:167], v[56:59]
	v_mfma_f32_16x16x32_bf16 v[44:47], v[132:135], v[172:175], v[44:47]
	v_mfma_f32_16x16x32_bf16 v[40:43], v[140:143], v[172:175], v[40:43]
	v_mfma_f32_16x16x32_bf16 v[28:31], v[132:135], v[196:199], v[28:31]
	v_mfma_f32_16x16x32_bf16 v[24:27], v[140:143], v[196:199], v[24:27]
	v_mfma_f32_16x16x32_bf16 v[12:15], v[132:135], v[210:213], v[12:15]
	v_mfma_f32_16x16x32_bf16 v[8:11], v[140:143], v[210:213], v[8:11]
	s_setprio 0
	s_setprio 1
	v_mfma_f32_16x16x32_bf16 v[52:55], v[144:147], v[160:163], v[52:55]
	v_mfma_f32_16x16x32_bf16 v[48:51], v[152:155], v[160:163], v[48:51]
	v_mfma_f32_16x16x32_bf16 v[36:39], v[144:147], v[168:171], v[36:39]
	v_mfma_f32_16x16x32_bf16 v[32:35], v[152:155], v[168:171], v[32:35]
	v_mfma_f32_16x16x32_bf16 v[20:23], v[144:147], v[192:195], v[20:23]
	v_mfma_f32_16x16x32_bf16 v[16:19], v[152:155], v[192:195], v[16:19]
	v_mfma_f32_16x16x32_bf16 v[4:7], v[144:147], v[200:203], v[4:7]
	v_mfma_f32_16x16x32_bf16 v[0:3], v[152:155], v[200:203], v[0:3]
	v_mfma_f32_16x16x32_bf16 v[52:55], v[148:151], v[164:167], v[52:55]
	v_mfma_f32_16x16x32_bf16 v[48:51], v[156:159], v[164:167], v[48:51]
	v_mfma_f32_16x16x32_bf16 v[36:39], v[148:151], v[172:175], v[36:39]
	v_mfma_f32_16x16x32_bf16 v[32:35], v[156:159], v[172:175], v[32:35]
	v_mfma_f32_16x16x32_bf16 v[20:23], v[148:151], v[196:199], v[20:23]
	v_mfma_f32_16x16x32_bf16 v[16:19], v[156:159], v[196:199], v[16:19]
	v_mfma_f32_16x16x32_bf16 v[4:7], v[148:151], v[210:213], v[4:7]
	v_mfma_f32_16x16x32_bf16 v[0:3], v[156:159], v[210:213], v[0:3]
	s_barrier
	s_setprio 0
	s_add_i32 s69, s69, 2
	s_add_u32 s30, s30, 0x100
	s_addc_u32 s31, s31, 0
	s_add_u32 s65, s65, 0x100
	s_addc_u32 s68, s68, 0
	s_cmp_gt_u32 s69, 13
	s_cbranch_scc0 .LBB0_471
	s_and_b64 vcc, exec, s[16:17]
	s_cbranch_vccz .LBB0_474
	s_barrier

.LBB0_555:
	s_add_u32 s30, s28, 0xfffc0080
	s_addc_u32 s31, s29, -1
	s_cmp_eq_u32 s63, 12
	s_cselect_b32 s35, s19, s31
	s_cselect_b32 s34, s51, s30
	s_cselect_b32 s31, s17, s62
	s_cselect_b32 s30, s60, s61
	v_lshl_add_u64 v[144:145], s[28:29], 0, v[136:137]
	s_add_i32 m0, s25, 0xc000
	s_nop 0
	global_load_lds_dwordx4 v[144:145], off
	ds_read_b128 v[154:157], v149
	ds_read_b128 v[158:161], v149 offset:1024
	ds_read_b128 v[162:165], v149 offset:2048
	ds_read_b128 v[166:169], v149 offset:3072
	ds_read_b128 v[170:173], v150
	ds_read_b128 v[174:177], v150 offset:1024
	ds_read_b128 v[178:181], v150 offset:2048
	ds_read_b128 v[182:185], v150 offset:3072
	v_lshl_add_u64 v[144:145], s[28:29], 0, v[138:139]
	s_add_i32 m0, s25, 0xe000
	s_nop 0
	global_load_lds_dwordx4 v[144:145], off
	ds_read_b128 v[186:189], v151
	ds_read_b128 v[190:193], v151 offset:1024
	ds_read_b128 v[194:197], v151 offset:2048
	ds_read_b128 v[198:201], v151 offset:3072
	ds_read_b128 v[202:205], v151 offset:4096
	ds_read_b128 v[206:209], v151 offset:5120
	ds_read_b128 v[210:213], v151 offset:6144
	ds_read_b128 v[214:217], v151 offset:7168
	s_waitcnt vmcnt(8)
	s_waitcnt lgkmcnt(0)
	s_setprio 1
	s_barrier
	v_mfma_f32_16x16x32_bf16 v[116:119], v[154:157], v[186:189], v[116:119]
	v_mfma_f32_16x16x32_bf16 v[112:115], v[162:165], v[186:189], v[112:115]
	v_mfma_f32_16x16x32_bf16 v[108:111], v[154:157], v[194:197], v[108:111]
	v_mfma_f32_16x16x32_bf16 v[100:103], v[162:165], v[194:197], v[100:103]
	v_mfma_f32_16x16x32_bf16 v[92:95], v[154:157], v[202:205], v[92:95]
	v_mfma_f32_16x16x32_bf16 v[84:87], v[162:165], v[202:205], v[84:87]
	v_mfma_f32_16x16x32_bf16 v[76:79], v[154:157], v[210:213], v[76:79]
	v_mfma_f32_16x16x32_bf16 v[68:71], v[162:165], v[210:213], v[68:71]
	v_mfma_f32_16x16x32_bf16 v[116:119], v[158:161], v[190:193], v[116:119]
	v_mfma_f32_16x16x32_bf16 v[112:115], v[166:169], v[190:193], v[112:115]
	v_mfma_f32_16x16x32_bf16 v[108:111], v[158:161], v[198:201], v[108:111]
	v_mfma_f32_16x16x32_bf16 v[100:103], v[166:169], v[198:201], v[100:103]
	v_mfma_f32_16x16x32_bf16 v[92:95], v[158:161], v[206:209], v[92:95]
	v_mfma_f32_16x16x32_bf16 v[84:87], v[166:169], v[206:209], v[84:87]
	v_mfma_f32_16x16x32_bf16 v[76:79], v[158:161], v[214:217], v[76:79]
	v_mfma_f32_16x16x32_bf16 v[68:71], v[166:169], v[214:217], v[68:71]
	s_setprio 0
	s_setprio 1
	v_mfma_f32_16x16x32_bf16 v[124:127], v[170:173], v[186:189], v[124:127]
	v_mfma_f32_16x16x32_bf16 v[120:123], v[178:181], v[186:189], v[120:123]
	v_mfma_f32_16x16x32_bf16 v[104:107], v[170:173], v[194:197], v[104:107]
	v_mfma_f32_16x16x32_bf16 v[96:99], v[178:181], v[194:197], v[96:99]
	v_mfma_f32_16x16x32_bf16 v[88:91], v[170:173], v[202:205], v[88:91]
	v_mfma_f32_16x16x32_bf16 v[80:83], v[178:181], v[202:205], v[80:83]
	v_mfma_f32_16x16x32_bf16 v[72:75], v[170:173], v[210:213], v[72:75]
	v_mfma_f32_16x16x32_bf16 v[64:67], v[178:181], v[210:213], v[64:67]
	v_mfma_f32_16x16x32_bf16 v[124:127], v[174:177], v[190:193], v[124:127]
	v_mfma_f32_16x16x32_bf16 v[120:123], v[182:185], v[190:193], v[120:123]
	v_mfma_f32_16x16x32_bf16 v[104:107], v[174:177], v[198:201], v[104:107]
	v_mfma_f32_16x16x32_bf16 v[96:99], v[182:185], v[198:201], v[96:99]
	v_mfma_f32_16x16x32_bf16 v[88:91], v[174:177], v[206:209], v[88:91]
	v_mfma_f32_16x16x32_bf16 v[80:83], v[182:185], v[206:209], v[80:83]
	v_mfma_f32_16x16x32_bf16 v[72:75], v[174:177], v[214:217], v[72:75]
	v_mfma_f32_16x16x32_bf16 v[64:67], v[182:185], v[214:217], v[64:67]
	s_barrier
	s_setprio 0
	s_add_i32 s64, s48, s36
	v_lshl_add_u64 v[144:145], s[30:31], 0, v[132:133]
	s_mov_b32 m0, s64
	s_nop 0
	global_load_lds_dwordx4 v[144:145], off
	ds_read_b128 v[186:189], v151 offset:16384
	ds_read_b128 v[190:193], v151 offset:17408
	s_add_i32 m0, s64, 0x2000
	s_add_u32 s64, s30, 0x40000
	v_lshl_add_u64 v[218:219], s[30:31], 0, v[128:129]
	s_addc_u32 s65, s31, 0
	s_add_i32 s68, s49, s36
	global_load_lds_dwordx4 v[218:219], off
	ds_read_b128 v[194:197], v151 offset:18432
	ds_read_b128 v[198:201], v151 offset:19456
	v_lshl_add_u64 v[220:221], s[64:65], 0, v[132:133]
	s_mov_b32 m0, s68
	v_lshl_add_u64 v[222:223], s[34:35], 0, v[130:131]
	global_load_lds_dwordx4 v[220:221], off
	ds_read_b128 v[202:205], v151 offset:20480
	ds_read_b128 v[206:209], v151 offset:21504
	v_lshl_add_u64 v[220:221], s[64:65], 0, v[128:129]
	s_add_i32 m0, s68, 0x2000
	s_nop 0
	global_load_lds_dwordx4 v[220:221], off
	ds_read_b128 v[210:213], v151 offset:22528
	ds_read_b128 v[214:217], v151 offset:23552
	v_lshl_add_u64 v[220:221], s[34:35], 0, v[134:135]
	s_mov_b32 m0, s25
	s_nop 0
	global_load_lds_dwordx4 v[220:221], off
	s_mov_b32 m0, s27
	s_nop 0
	global_load_lds_dwordx4 v[222:223], off
	s_waitcnt vmcnt(8)
	s_waitcnt lgkmcnt(0)
	s_setprio 1
	s_barrier
	v_mfma_f32_16x16x32_bf16 v[60:63], v[154:157], v[186:189], v[60:63]
	v_mfma_f32_16x16x32_bf16 v[52:55], v[162:165], v[186:189], v[52:55]
	v_mfma_f32_16x16x32_bf16 v[44:47], v[154:157], v[194:197], v[44:47]
	v_mfma_f32_16x16x32_bf16 v[36:39], v[162:165], v[194:197], v[36:39]
	v_mfma_f32_16x16x32_bf16 v[28:31], v[154:157], v[202:205], v[28:31]
	v_mfma_f32_16x16x32_bf16 v[20:23], v[162:165], v[202:205], v[20:23]
	v_mfma_f32_16x16x32_bf16 v[12:15], v[154:157], v[210:213], v[12:15]
	v_mfma_f32_16x16x32_bf16 v[4:7], v[162:165], v[210:213], v[4:7]
	v_mfma_f32_16x16x32_bf16 v[60:63], v[158:161], v[190:193], v[60:63]
	v_mfma_f32_16x16x32_bf16 v[52:55], v[166:169], v[190:193], v[52:55]
	v_mfma_f32_16x16x32_bf16 v[44:47], v[158:161], v[198:201], v[44:47]
	v_mfma_f32_16x16x32_bf16 v[36:39], v[166:169], v[198:201], v[36:39]
	v_mfma_f32_16x16x32_bf16 v[28:31], v[158:161], v[206:209], v[28:31]
	v_mfma_f32_16x16x32_bf16 v[20:23], v[166:169], v[206:209], v[20:23]
	v_mfma_f32_16x16x32_bf16 v[12:15], v[158:161], v[214:217], v[12:15]
	v_mfma_f32_16x16x32_bf16 v[4:7], v[166:169], v[214:217], v[4:7]
	s_setprio 0
	s_setprio 1
	v_mfma_f32_16x16x32_bf16 v[56:59], v[170:173], v[186:189], v[56:59]
	v_mfma_f32_16x16x32_bf16 v[48:51], v[178:181], v[186:189], v[48:51]
	v_mfma_f32_16x16x32_bf16 v[40:43], v[170:173], v[194:197], v[40:43]
	v_mfma_f32_16x16x32_bf16 v[32:35], v[178:181], v[194:197], v[32:35]
	v_mfma_f32_16x16x32_bf16 v[24:27], v[170:173], v[202:205], v[24:27]
	v_mfma_f32_16x16x32_bf16 v[16:19], v[178:181], v[202:205], v[16:19]
	v_mfma_f32_16x16x32_bf16 v[8:11], v[170:173], v[210:213], v[8:11]
	v_mfma_f32_16x16x32_bf16 v[0:3], v[178:181], v[210:213], v[0:3]
	v_mfma_f32_16x16x32_bf16 v[56:59], v[174:177], v[190:193], v[56:59]
	v_mfma_f32_16x16x32_bf16 v[48:51], v[182:185], v[190:193], v[48:51]
	v_mfma_f32_16x16x32_bf16 v[40:43], v[174:177], v[198:201], v[40:43]
	v_mfma_f32_16x16x32_bf16 v[32:35], v[182:185], v[198:201], v[32:35]
	v_mfma_f32_16x16x32_bf16 v[24:27], v[174:177], v[206:209], v[24:27]
	v_mfma_f32_16x16x32_bf16 v[16:19], v[182:185], v[206:209], v[16:19]
	v_mfma_f32_16x16x32_bf16 v[8:11], v[174:177], v[214:217], v[8:11]
	v_mfma_f32_16x16x32_bf16 v[0:3], v[182:185], v[214:217], v[0:3]
	s_barrier
	s_setprio 0
	s_add_i32 s64, 0, 0x18000
	s_add_i32 s65, 0, 0x1c000
	s_add_u32 s34, s34, 0x40000
	s_addc_u32 s35, s35, 0
	s_mov_b32 m0, s39
	v_lshl_add_u64 v[224:225], s[34:35], 0, v[134:135]
	global_load_lds_dwordx4 v[224:225], off
	v_add_u32_e32 v153, s64, v147
	ds_read_b128 v[154:157], v153
	ds_read_b128 v[158:161], v153 offset:1024
	ds_read_b128 v[162:165], v153 offset:2048
	ds_read_b128 v[166:169], v153 offset:3072
	v_add_u32_e32 v153, s65, v147
	ds_read_b128 v[170:173], v153
	ds_read_b128 v[174:177], v153 offset:1024
	ds_read_b128 v[178:181], v153 offset:2048
	ds_read_b128 v[182:185], v153 offset:3072
	v_lshl_add_u64 v[224:225], s[34:35], 0, v[130:131]
	s_mov_b32 m0, s40
	s_nop 0
	global_load_lds_dwordx4 v[224:225], off
	ds_read_b128 v[186:189], v151 offset:32768
	ds_read_b128 v[190:193], v151 offset:33792
	ds_read_b128 v[194:197], v151 offset:34816
	ds_read_b128 v[198:201], v151 offset:35840
	ds_read_b128 v[202:205], v151 offset:36864
	ds_read_b128 v[206:209], v151 offset:37888
	ds_read_b128 v[210:213], v151 offset:38912
	ds_read_b128 v[214:217], v151 offset:39936
	s_waitcnt vmcnt(8)
	s_waitcnt lgkmcnt(0)
	s_setprio 1
	s_barrier
	v_mfma_f32_16x16x32_bf16 v[116:119], v[154:157], v[186:189], v[116:119]
	v_mfma_f32_16x16x32_bf16 v[112:115], v[162:165], v[186:189], v[112:115]
	v_mfma_f32_16x16x32_bf16 v[108:111], v[154:157], v[194:197], v[108:111]
	v_mfma_f32_16x16x32_bf16 v[100:103], v[162:165], v[194:197], v[100:103]
	v_mfma_f32_16x16x32_bf16 v[92:95], v[154:157], v[202:205], v[92:95]
	v_mfma_f32_16x16x32_bf16 v[84:87], v[162:165], v[202:205], v[84:87]
	v_mfma_f32_16x16x32_bf16 v[76:79], v[154:157], v[210:213], v[76:79]
	v_mfma_f32_16x16x32_bf16 v[68:71], v[162:165], v[210:213], v[68:71]
	v_mfma_f32_16x16x32_bf16 v[116:119], v[158:161], v[190:193], v[116:119]
	v_mfma_f32_16x16x32_bf16 v[112:115], v[166:169], v[190:193], v[112:115]
	v_mfma_f32_16x16x32_bf16 v[108:111], v[158:161], v[198:201], v[108:111]
	v_mfma_f32_16x16x32_bf16 v[100:103], v[166:169], v[198:201], v[100:103]
	v_mfma_f32_16x16x32_bf16 v[92:95], v[158:161], v[206:209], v[92:95]
	v_mfma_f32_16x16x32_bf16 v[84:87], v[166:169], v[206:209], v[84:87]
	v_mfma_f32_16x16x32_bf16 v[76:79], v[158:161], v[214:217], v[76:79]
	v_mfma_f32_16x16x32_bf16 v[68:71], v[166:169], v[214:217], v[68:71]
	s_setprio 0
	s_setprio 1
	v_mfma_f32_16x16x32_bf16 v[124:127], v[170:173], v[186:189], v[124:127]
	v_mfma_f32_16x16x32_bf16 v[120:123], v[178:181], v[186:189], v[120:123]
	v_mfma_f32_16x16x32_bf16 v[104:107], v[170:173], v[194:197], v[104:107]
	v_mfma_f32_16x16x32_bf16 v[96:99], v[178:181], v[194:197], v[96:99]
	v_mfma_f32_16x16x32_bf16 v[88:91], v[170:173], v[202:205], v[88:91]
	v_mfma_f32_16x16x32_bf16 v[80:83], v[178:181], v[202:205], v[80:83]
	v_mfma_f32_16x16x32_bf16 v[72:75], v[170:173], v[210:213], v[72:75]
	v_mfma_f32_16x16x32_bf16 v[64:67], v[178:181], v[210:213], v[64:67]
	v_mfma_f32_16x16x32_bf16 v[124:127], v[174:177], v[190:193], v[124:127]
	v_mfma_f32_16x16x32_bf16 v[120:123], v[182:185], v[190:193], v[120:123]
	v_mfma_f32_16x16x32_bf16 v[104:107], v[174:177], v[198:201], v[104:107]
	v_mfma_f32_16x16x32_bf16 v[96:99], v[182:185], v[198:201], v[96:99]
	v_mfma_f32_16x16x32_bf16 v[88:91], v[174:177], v[206:209], v[88:91]
	v_mfma_f32_16x16x32_bf16 v[80:83], v[182:185], v[206:209], v[80:83]
	v_mfma_f32_16x16x32_bf16 v[72:75], v[174:177], v[214:217], v[72:75]
	v_mfma_f32_16x16x32_bf16 v[64:67], v[182:185], v[214:217], v[64:67]
	s_barrier
	s_setprio 0
	s_add_i32 s34, s64, s36
	v_lshl_add_u64 v[144:145], v[144:145], 0, s[12:13]
	s_mov_b32 m0, s34
	s_nop 0
	global_load_lds_dwordx4 v[144:145], off
	ds_read_b128 v[186:189], v151 offset:49152
	ds_read_b128 v[190:193], v151 offset:50176
	s_add_i32 m0, s34, 0x2000
	s_add_u32 s30, s30, 0x40080
	v_lshl_add_u64 v[144:145], v[218:219], 0, s[12:13]
	s_addc_u32 s31, s31, 0
	s_add_i32 s34, s65, s36
	global_load_lds_dwordx4 v[144:145], off
	ds_read_b128 v[194:197], v151 offset:51200
	ds_read_b128 v[198:201], v151 offset:52224
	v_lshl_add_u64 v[144:145], s[30:31], 0, v[132:133]
	s_mov_b32 m0, s34
	s_nop 0
	global_load_lds_dwordx4 v[144:145], off
	ds_read_b128 v[202:205], v151 offset:53248
	ds_read_b128 v[206:209], v151 offset:54272
	v_lshl_add_u64 v[144:145], s[30:31], 0, v[128:129]
	s_add_i32 m0, s34, 0x2000
	s_nop 0
	global_load_lds_dwordx4 v[144:145], off
	ds_read_b128 v[210:213], v151 offset:55296
	ds_read_b128 v[214:217], v151 offset:56320
	v_lshl_add_u64 v[144:145], v[220:221], 0, s[12:13]
	s_mov_b32 m0, s42
	s_nop 0
	global_load_lds_dwordx4 v[144:145], off
	v_lshl_add_u64 v[144:145], v[222:223], 0, s[12:13]
	s_mov_b32 m0, s43
	s_nop 0
	global_load_lds_dwordx4 v[144:145], off
	s_waitcnt vmcnt(8)
	s_waitcnt lgkmcnt(0)
	s_setprio 1
	s_barrier
	v_mfma_f32_16x16x32_bf16 v[60:63], v[154:157], v[186:189], v[60:63]
	v_mfma_f32_16x16x32_bf16 v[52:55], v[162:165], v[186:189], v[52:55]
	v_mfma_f32_16x16x32_bf16 v[44:47], v[154:157], v[194:197], v[44:47]
	v_mfma_f32_16x16x32_bf16 v[36:39], v[162:165], v[194:197], v[36:39]
	v_mfma_f32_16x16x32_bf16 v[28:31], v[154:157], v[202:205], v[28:31]
	v_mfma_f32_16x16x32_bf16 v[20:23], v[162:165], v[202:205], v[20:23]
	v_mfma_f32_16x16x32_bf16 v[12:15], v[154:157], v[210:213], v[12:15]
	v_mfma_f32_16x16x32_bf16 v[4:7], v[162:165], v[210:213], v[4:7]
	v_mfma_f32_16x16x32_bf16 v[60:63], v[158:161], v[190:193], v[60:63]
	v_mfma_f32_16x16x32_bf16 v[52:55], v[166:169], v[190:193], v[52:55]
	v_mfma_f32_16x16x32_bf16 v[44:47], v[158:161], v[198:201], v[44:47]
	v_mfma_f32_16x16x32_bf16 v[36:39], v[166:169], v[198:201], v[36:39]
	v_mfma_f32_16x16x32_bf16 v[28:31], v[158:161], v[206:209], v[28:31]
	v_mfma_f32_16x16x32_bf16 v[20:23], v[166:169], v[206:209], v[20:23]
	v_mfma_f32_16x16x32_bf16 v[12:15], v[158:161], v[214:217], v[12:15]
	v_mfma_f32_16x16x32_bf16 v[4:7], v[166:169], v[214:217], v[4:7]
	s_setprio 0
	s_setprio 1
	v_mfma_f32_16x16x32_bf16 v[56:59], v[170:173], v[186:189], v[56:59]
	v_mfma_f32_16x16x32_bf16 v[48:51], v[178:181], v[186:189], v[48:51]
	v_mfma_f32_16x16x32_bf16 v[40:43], v[170:173], v[194:197], v[40:43]
	v_mfma_f32_16x16x32_bf16 v[32:35], v[178:181], v[194:197], v[32:35]
	v_mfma_f32_16x16x32_bf16 v[24:27], v[170:173], v[202:205], v[24:27]
	v_mfma_f32_16x16x32_bf16 v[16:19], v[178:181], v[202:205], v[16:19]
	v_mfma_f32_16x16x32_bf16 v[8:11], v[170:173], v[210:213], v[8:11]
	v_mfma_f32_16x16x32_bf16 v[0:3], v[178:181], v[210:213], v[0:3]
	v_mfma_f32_16x16x32_bf16 v[56:59], v[174:177], v[190:193], v[56:59]
	v_mfma_f32_16x16x32_bf16 v[48:51], v[182:185], v[190:193], v[48:51]
	v_mfma_f32_16x16x32_bf16 v[40:43], v[174:177], v[198:201], v[40:43]
	v_mfma_f32_16x16x32_bf16 v[32:35], v[182:185], v[198:201], v[32:35]
	v_mfma_f32_16x16x32_bf16 v[24:27], v[174:177], v[206:209], v[24:27]
	v_mfma_f32_16x16x32_bf16 v[16:19], v[182:185], v[206:209], v[16:19]
	v_mfma_f32_16x16x32_bf16 v[8:11], v[174:177], v[214:217], v[8:11]
	v_mfma_f32_16x16x32_bf16 v[0:3], v[182:185], v[214:217], v[0:3]
	s_barrier
	s_setprio 0
	s_add_i32 s63, s63, 2
	s_add_u32 s28, s28, 0x100
	s_addc_u32 s29, s29, 0
	s_add_u32 s61, s61, 0x100
	s_addc_u32 s62, s62, 0
	s_cmp_gt_u32 s63, 13
	s_cbranch_scc0 .LBB0_555
	s_and_b64 vcc, exec, s[14:15]
	s_cbranch_vccz .LBB0_558
	s_barrier

.LBB0_637:
	s_add_u32 s22, s20, 0x100
	s_addc_u32 s23, s21, 0
	s_cmp_eq_u32 s61, 40
	s_cselect_b32 s27, s9, s23
	s_cselect_b32 s26, s8, s22
	s_cselect_b32 s25, s19, s60
	s_cselect_b32 s24, s18, s51
	v_lshl_add_u64 v[206:207], s[20:21], 0, v[200:201]
	s_add_i32 m0, s29, 0xc000
	s_nop 0
	global_load_lds_dwordx4 v[206:207], off
	ds_read_b128 v[120:123], v247
	ds_read_b128 v[124:127], v247 offset:1024
	ds_read_b128 v[128:131], v247 offset:2048
	ds_read_b128 v[132:135], v247 offset:3072
	ds_read_b128 v[140:143], v248
	ds_read_b128 v[148:151], v248 offset:1024
	ds_read_b128 v[152:155], v248 offset:2048
	ds_read_b128 v[156:159], v248 offset:3072
	v_lshl_add_u64 v[206:207], s[20:21], 0, v[202:203]
	s_add_i32 m0, s29, 0xe000
	s_nop 0
	global_load_lds_dwordx4 v[206:207], off
	ds_read_b128 v[160:163], v249
	ds_read_b128 v[164:167], v249 offset:1024
	ds_read_b128 v[168:171], v249 offset:2048
	ds_read_b128 v[172:175], v249 offset:3072
	ds_read_b128 v[176:179], v249 offset:4096
	ds_read_b128 v[180:183], v249 offset:5120
	ds_read_b128 v[184:187], v249 offset:6144
	ds_read_b128 v[188:191], v249 offset:7168
	s_waitcnt vmcnt(8)
	s_waitcnt lgkmcnt(0)
	s_setprio 1
	s_barrier
	v_mfma_f32_16x16x32_bf16 v[144:147], v[120:123], v[160:163], v[144:147]
	v_mfma_f32_16x16x32_bf16 v[136:139], v[128:131], v[160:163], v[136:139]
	v_mfma_f32_16x16x32_bf16 v[108:111], v[120:123], v[168:171], v[108:111]
	v_mfma_f32_16x16x32_bf16 v[104:107], v[128:131], v[168:171], v[104:107]
	v_mfma_f32_16x16x32_bf16 v[92:95], v[120:123], v[176:179], v[92:95]
	v_mfma_f32_16x16x32_bf16 v[88:91], v[128:131], v[176:179], v[88:91]
	v_mfma_f32_16x16x32_bf16 v[76:79], v[120:123], v[184:187], v[76:79]
	v_mfma_f32_16x16x32_bf16 v[72:75], v[128:131], v[184:187], v[72:75]
	v_mfma_f32_16x16x32_bf16 v[144:147], v[124:127], v[164:167], v[144:147]
	v_mfma_f32_16x16x32_bf16 v[136:139], v[132:135], v[164:167], v[136:139]
	v_mfma_f32_16x16x32_bf16 v[108:111], v[124:127], v[172:175], v[108:111]
	v_mfma_f32_16x16x32_bf16 v[104:107], v[132:135], v[172:175], v[104:107]
	v_mfma_f32_16x16x32_bf16 v[92:95], v[124:127], v[180:183], v[92:95]
	v_mfma_f32_16x16x32_bf16 v[88:91], v[132:135], v[180:183], v[88:91]
	v_mfma_f32_16x16x32_bf16 v[76:79], v[124:127], v[188:191], v[76:79]
	v_mfma_f32_16x16x32_bf16 v[72:75], v[132:135], v[188:191], v[72:75]
	s_setprio 0
	s_setprio 1
	v_mfma_f32_16x16x32_bf16 v[116:119], v[140:143], v[160:163], v[116:119]
	v_mfma_f32_16x16x32_bf16 v[112:115], v[152:155], v[160:163], v[112:115]
	v_mfma_f32_16x16x32_bf16 v[100:103], v[140:143], v[168:171], v[100:103]
	v_mfma_f32_16x16x32_bf16 v[96:99], v[152:155], v[168:171], v[96:99]
	v_mfma_f32_16x16x32_bf16 v[84:87], v[140:143], v[176:179], v[84:87]
	v_mfma_f32_16x16x32_bf16 v[80:83], v[152:155], v[176:179], v[80:83]
	v_mfma_f32_16x16x32_bf16 v[68:71], v[140:143], v[184:187], v[68:71]
	v_mfma_f32_16x16x32_bf16 v[64:67], v[152:155], v[184:187], v[64:67]
	v_mfma_f32_16x16x32_bf16 v[116:119], v[148:151], v[164:167], v[116:119]
	v_mfma_f32_16x16x32_bf16 v[112:115], v[156:159], v[164:167], v[112:115]
	v_mfma_f32_16x16x32_bf16 v[100:103], v[148:151], v[172:175], v[100:103]
	v_mfma_f32_16x16x32_bf16 v[96:99], v[156:159], v[172:175], v[96:99]
	v_mfma_f32_16x16x32_bf16 v[84:87], v[148:151], v[180:183], v[84:87]
	v_mfma_f32_16x16x32_bf16 v[80:83], v[156:159], v[180:183], v[80:83]
	v_mfma_f32_16x16x32_bf16 v[68:71], v[148:151], v[188:191], v[68:71]
	v_mfma_f32_16x16x32_bf16 v[64:67], v[156:159], v[188:191], v[64:67]
	s_barrier
	s_setprio 0
	s_add_i32 s20, s43, s28
	v_lshl_add_u64 v[206:207], s[24:25], 0, v[194:195]
	s_mov_b32 m0, s20
	s_nop 0
	global_load_lds_dwordx4 v[206:207], off
	ds_read_b128 v[160:163], v249 offset:16384
	ds_read_b128 v[164:167], v249 offset:17408
	s_add_i32 m0, s20, 0x2000
	s_add_u32 s20, s24, 0xb0000
	v_lshl_add_u64 v[208:209], s[24:25], 0, v[198:199]
	s_addc_u32 s21, s25, 0
	s_add_i32 s62, s46, s28
	global_load_lds_dwordx4 v[208:209], off
	ds_read_b128 v[168:171], v249 offset:18432
	ds_read_b128 v[172:175], v249 offset:19456
	v_lshl_add_u64 v[210:211], s[20:21], 0, v[194:195]
	s_mov_b32 m0, s62
	v_lshl_add_u64 v[212:213], s[26:27], 0, v[196:197]
	global_load_lds_dwordx4 v[210:211], off
	ds_read_b128 v[176:179], v249 offset:20480
	ds_read_b128 v[180:183], v249 offset:21504
	v_lshl_add_u64 v[210:211], s[20:21], 0, v[198:199]
	s_add_i32 m0, s62, 0x2000
	s_nop 0
	global_load_lds_dwordx4 v[210:211], off
	ds_read_b128 v[184:187], v249 offset:22528
	ds_read_b128 v[188:191], v249 offset:23552
	v_lshl_add_u64 v[210:211], s[26:27], 0, v[192:193]
	s_mov_b32 m0, s29
	s_nop 0
	global_load_lds_dwordx4 v[210:211], off
	s_mov_b32 m0, s30
	s_nop 0
	global_load_lds_dwordx4 v[212:213], off
	s_waitcnt vmcnt(8)
	s_waitcnt lgkmcnt(0)
	s_setprio 1
	s_barrier
	v_mfma_f32_16x16x32_bf16 v[60:63], v[120:123], v[160:163], v[60:63]
	v_mfma_f32_16x16x32_bf16 v[56:59], v[128:131], v[160:163], v[56:59]
	v_mfma_f32_16x16x32_bf16 v[44:47], v[120:123], v[168:171], v[44:47]
	v_mfma_f32_16x16x32_bf16 v[40:43], v[128:131], v[168:171], v[40:43]
	v_mfma_f32_16x16x32_bf16 v[28:31], v[120:123], v[176:179], v[28:31]
	v_mfma_f32_16x16x32_bf16 v[24:27], v[128:131], v[176:179], v[24:27]
	v_mfma_f32_16x16x32_bf16 v[12:15], v[120:123], v[184:187], v[12:15]
	v_mfma_f32_16x16x32_bf16 v[8:11], v[128:131], v[184:187], v[8:11]
	v_mfma_f32_16x16x32_bf16 v[60:63], v[124:127], v[164:167], v[60:63]
	v_mfma_f32_16x16x32_bf16 v[56:59], v[132:135], v[164:167], v[56:59]
	v_mfma_f32_16x16x32_bf16 v[44:47], v[124:127], v[172:175], v[44:47]
	v_mfma_f32_16x16x32_bf16 v[40:43], v[132:135], v[172:175], v[40:43]
	v_mfma_f32_16x16x32_bf16 v[28:31], v[124:127], v[180:183], v[28:31]
	v_mfma_f32_16x16x32_bf16 v[24:27], v[132:135], v[180:183], v[24:27]
	v_mfma_f32_16x16x32_bf16 v[12:15], v[124:127], v[188:191], v[12:15]
	v_mfma_f32_16x16x32_bf16 v[8:11], v[132:135], v[188:191], v[8:11]
	s_setprio 0
	s_setprio 1
	v_mfma_f32_16x16x32_bf16 v[52:55], v[140:143], v[160:163], v[52:55]
	v_mfma_f32_16x16x32_bf16 v[48:51], v[152:155], v[160:163], v[48:51]
	v_mfma_f32_16x16x32_bf16 v[36:39], v[140:143], v[168:171], v[36:39]
	v_mfma_f32_16x16x32_bf16 v[32:35], v[152:155], v[168:171], v[32:35]
	v_mfma_f32_16x16x32_bf16 v[20:23], v[140:143], v[176:179], v[20:23]
	v_mfma_f32_16x16x32_bf16 v[16:19], v[152:155], v[176:179], v[16:19]
	v_mfma_f32_16x16x32_bf16 v[4:7], v[140:143], v[184:187], v[4:7]
	v_mfma_f32_16x16x32_bf16 v[0:3], v[152:155], v[184:187], v[0:3]
	v_mfma_f32_16x16x32_bf16 v[52:55], v[148:151], v[164:167], v[52:55]
	v_mfma_f32_16x16x32_bf16 v[48:51], v[156:159], v[164:167], v[48:51]
	v_mfma_f32_16x16x32_bf16 v[36:39], v[148:151], v[172:175], v[36:39]
	v_mfma_f32_16x16x32_bf16 v[32:35], v[156:159], v[172:175], v[32:35]
	v_mfma_f32_16x16x32_bf16 v[20:23], v[148:151], v[180:183], v[20:23]
	v_mfma_f32_16x16x32_bf16 v[16:19], v[156:159], v[180:183], v[16:19]
	v_mfma_f32_16x16x32_bf16 v[4:7], v[148:151], v[188:191], v[4:7]
	v_mfma_f32_16x16x32_bf16 v[0:3], v[156:159], v[188:191], v[0:3]
	s_barrier
	s_setprio 0
	s_add_i32 s62, 0, 0x18000
	s_add_i32 s63, 0, 0x1c000
	s_add_u32 s20, s26, 0xb0000
	s_addc_u32 s21, s27, 0
	s_mov_b32 m0, s31
	v_lshl_add_u64 v[214:215], s[20:21], 0, v[192:193]
	global_load_lds_dwordx4 v[214:215], off
	v_add_u32_e32 v132, s62, v246
	v_add_u32_e32 v156, s63, v246
	ds_read_b128 v[120:123], v132
	ds_read_b128 v[124:127], v132 offset:1024
	ds_read_b128 v[128:131], v132 offset:2048
	ds_read_b128 v[132:135], v132 offset:3072
	ds_read_b128 v[140:143], v156
	ds_read_b128 v[148:151], v156 offset:1024
	ds_read_b128 v[152:155], v156 offset:2048
	ds_read_b128 v[156:159], v156 offset:3072
	v_lshl_add_u64 v[214:215], s[20:21], 0, v[196:197]
	s_mov_b32 m0, s34
	s_nop 0
	global_load_lds_dwordx4 v[214:215], off
	ds_read_b128 v[160:163], v249 offset:32768
	ds_read_b128 v[164:167], v249 offset:33792
	ds_read_b128 v[168:171], v249 offset:34816
	ds_read_b128 v[172:175], v249 offset:35840
	ds_read_b128 v[176:179], v249 offset:36864
	ds_read_b128 v[180:183], v249 offset:37888
	ds_read_b128 v[184:187], v249 offset:38912
	ds_read_b128 v[188:191], v249 offset:39936
	s_waitcnt vmcnt(8)
	s_waitcnt lgkmcnt(0)
	s_setprio 1
	s_barrier
	v_mfma_f32_16x16x32_bf16 v[144:147], v[120:123], v[160:163], v[144:147]
	v_mfma_f32_16x16x32_bf16 v[136:139], v[128:131], v[160:163], v[136:139]
	v_mfma_f32_16x16x32_bf16 v[108:111], v[120:123], v[168:171], v[108:111]
	v_mfma_f32_16x16x32_bf16 v[104:107], v[128:131], v[168:171], v[104:107]
	v_mfma_f32_16x16x32_bf16 v[92:95], v[120:123], v[176:179], v[92:95]
	v_mfma_f32_16x16x32_bf16 v[88:91], v[128:131], v[176:179], v[88:91]
	v_mfma_f32_16x16x32_bf16 v[76:79], v[120:123], v[184:187], v[76:79]
	v_mfma_f32_16x16x32_bf16 v[72:75], v[128:131], v[184:187], v[72:75]
	v_mfma_f32_16x16x32_bf16 v[144:147], v[124:127], v[164:167], v[144:147]
	v_mfma_f32_16x16x32_bf16 v[136:139], v[132:135], v[164:167], v[136:139]
	v_mfma_f32_16x16x32_bf16 v[108:111], v[124:127], v[172:175], v[108:111]
	v_mfma_f32_16x16x32_bf16 v[104:107], v[132:135], v[172:175], v[104:107]
	v_mfma_f32_16x16x32_bf16 v[92:95], v[124:127], v[180:183], v[92:95]
	v_mfma_f32_16x16x32_bf16 v[88:91], v[132:135], v[180:183], v[88:91]
	v_mfma_f32_16x16x32_bf16 v[76:79], v[124:127], v[188:191], v[76:79]
	v_mfma_f32_16x16x32_bf16 v[72:75], v[132:135], v[188:191], v[72:75]
	s_setprio 0
	s_setprio 1
	v_mfma_f32_16x16x32_bf16 v[116:119], v[140:143], v[160:163], v[116:119]
	v_mfma_f32_16x16x32_bf16 v[112:115], v[152:155], v[160:163], v[112:115]
	v_mfma_f32_16x16x32_bf16 v[100:103], v[140:143], v[168:171], v[100:103]
	v_mfma_f32_16x16x32_bf16 v[96:99], v[152:155], v[168:171], v[96:99]
	v_mfma_f32_16x16x32_bf16 v[84:87], v[140:143], v[176:179], v[84:87]
	v_mfma_f32_16x16x32_bf16 v[80:83], v[152:155], v[176:179], v[80:83]
	v_mfma_f32_16x16x32_bf16 v[68:71], v[140:143], v[184:187], v[68:71]
	v_mfma_f32_16x16x32_bf16 v[64:67], v[152:155], v[184:187], v[64:67]
	v_mfma_f32_16x16x32_bf16 v[116:119], v[148:151], v[164:167], v[116:119]
	v_mfma_f32_16x16x32_bf16 v[112:115], v[156:159], v[164:167], v[112:115]
	v_mfma_f32_16x16x32_bf16 v[100:103], v[148:151], v[172:175], v[100:103]
	v_mfma_f32_16x16x32_bf16 v[96:99], v[156:159], v[172:175], v[96:99]
	v_mfma_f32_16x16x32_bf16 v[84:87], v[148:151], v[180:183], v[84:87]
	v_mfma_f32_16x16x32_bf16 v[80:83], v[156:159], v[180:183], v[80:83]
	v_mfma_f32_16x16x32_bf16 v[68:71], v[148:151], v[188:191], v[68:71]
	v_mfma_f32_16x16x32_bf16 v[64:67], v[156:159], v[188:191], v[64:67]
	s_barrier
	s_setprio 0
	s_add_i32 s20, s62, s28
	v_lshl_add_u64 v[206:207], v[206:207], 0, s[14:15]
	s_mov_b32 m0, s20
	s_nop 0
	global_load_lds_dwordx4 v[206:207], off
	ds_read_b128 v[160:163], v249 offset:49152
	ds_read_b128 v[164:167], v249 offset:50176
	s_add_i32 m0, s20, 0x2000
	s_add_u32 s20, s24, 0xb0080
	v_lshl_add_u64 v[206:207], v[208:209], 0, s[14:15]
	s_addc_u32 s21, s25, 0
	s_add_i32 s24, s63, s28
	global_load_lds_dwordx4 v[206:207], off
	ds_read_b128 v[168:171], v249 offset:51200
	ds_read_b128 v[172:175], v249 offset:52224
	v_lshl_add_u64 v[206:207], s[20:21], 0, v[194:195]
	s_mov_b32 m0, s24
	s_nop 0
	global_load_lds_dwordx4 v[206:207], off
	ds_read_b128 v[176:179], v249 offset:53248
	ds_read_b128 v[180:183], v249 offset:54272
	v_lshl_add_u64 v[206:207], s[20:21], 0, v[198:199]
	s_add_i32 m0, s24, 0x2000
	s_nop 0
	global_load_lds_dwordx4 v[206:207], off
	ds_read_b128 v[184:187], v249 offset:55296
	ds_read_b128 v[188:191], v249 offset:56320
	v_lshl_add_u64 v[206:207], v[210:211], 0, s[14:15]
	s_mov_b32 m0, s38
	s_nop 0
	global_load_lds_dwordx4 v[206:207], off
	v_lshl_add_u64 v[206:207], v[212:213], 0, s[14:15]
	s_mov_b32 m0, s39
	s_nop 0
	global_load_lds_dwordx4 v[206:207], off
	s_waitcnt vmcnt(8)
	s_waitcnt lgkmcnt(0)
	s_setprio 1
	s_barrier
	v_mfma_f32_16x16x32_bf16 v[60:63], v[120:123], v[160:163], v[60:63]
	v_mfma_f32_16x16x32_bf16 v[56:59], v[128:131], v[160:163], v[56:59]
	v_mfma_f32_16x16x32_bf16 v[44:47], v[120:123], v[168:171], v[44:47]
	v_mfma_f32_16x16x32_bf16 v[40:43], v[128:131], v[168:171], v[40:43]
	v_mfma_f32_16x16x32_bf16 v[28:31], v[120:123], v[176:179], v[28:31]
	v_mfma_f32_16x16x32_bf16 v[24:27], v[128:131], v[176:179], v[24:27]
	v_mfma_f32_16x16x32_bf16 v[12:15], v[120:123], v[184:187], v[12:15]
	v_mfma_f32_16x16x32_bf16 v[8:11], v[128:131], v[184:187], v[8:11]
	v_mfma_f32_16x16x32_bf16 v[60:63], v[124:127], v[164:167], v[60:63]
	v_mfma_f32_16x16x32_bf16 v[56:59], v[132:135], v[164:167], v[56:59]
	v_mfma_f32_16x16x32_bf16 v[44:47], v[124:127], v[172:175], v[44:47]
	v_mfma_f32_16x16x32_bf16 v[40:43], v[132:135], v[172:175], v[40:43]
	v_mfma_f32_16x16x32_bf16 v[28:31], v[124:127], v[180:183], v[28:31]
	v_mfma_f32_16x16x32_bf16 v[24:27], v[132:135], v[180:183], v[24:27]
	v_mfma_f32_16x16x32_bf16 v[12:15], v[124:127], v[188:191], v[12:15]
	v_mfma_f32_16x16x32_bf16 v[8:11], v[132:135], v[188:191], v[8:11]
	s_setprio 0
	s_setprio 1
	v_mfma_f32_16x16x32_bf16 v[52:55], v[140:143], v[160:163], v[52:55]
	v_mfma_f32_16x16x32_bf16 v[48:51], v[152:155], v[160:163], v[48:51]
	v_mfma_f32_16x16x32_bf16 v[36:39], v[140:143], v[168:171], v[36:39]
	v_mfma_f32_16x16x32_bf16 v[32:35], v[152:155], v[168:171], v[32:35]
	v_mfma_f32_16x16x32_bf16 v[20:23], v[140:143], v[176:179], v[20:23]
	v_mfma_f32_16x16x32_bf16 v[16:19], v[152:155], v[176:179], v[16:19]
	v_mfma_f32_16x16x32_bf16 v[4:7], v[140:143], v[184:187], v[4:7]
	v_mfma_f32_16x16x32_bf16 v[0:3], v[152:155], v[184:187], v[0:3]
	v_mfma_f32_16x16x32_bf16 v[52:55], v[148:151], v[164:167], v[52:55]
	v_mfma_f32_16x16x32_bf16 v[48:51], v[156:159], v[164:167], v[48:51]
	v_mfma_f32_16x16x32_bf16 v[36:39], v[148:151], v[172:175], v[36:39]
	v_mfma_f32_16x16x32_bf16 v[32:35], v[156:159], v[172:175], v[32:35]
	v_mfma_f32_16x16x32_bf16 v[20:23], v[148:151], v[180:183], v[20:23]
	v_mfma_f32_16x16x32_bf16 v[16:19], v[156:159], v[180:183], v[16:19]
	v_mfma_f32_16x16x32_bf16 v[4:7], v[148:151], v[188:191], v[4:7]
	v_mfma_f32_16x16x32_bf16 v[0:3], v[156:159], v[188:191], v[0:3]
	s_barrier
	s_setprio 0
	s_add_i32 s61, s61, 2
	s_add_u32 s51, s51, 0x100
	s_addc_u32 s60, s60, 0
	s_cmp_gt_u32 s61, 41
	s_mov_b64 s[20:21], s[22:23]
	s_cbranch_scc0 .LBB0_637
	s_and_b64 vcc, exec, s[16:17]
	s_cbranch_vccz .LBB0_640
	s_barrier

.LBB0_723:
	s_add_u32 s62, s48, 0xfffc0080
	s_addc_u32 s63, s49, -1
	s_cmp_eq_u32 s93, 12
	s_cselect_b32 s65, s9, s63
	s_cselect_b32 s64, s41, s62
	s_cselect_b32 s63, s39, s61
	s_cselect_b32 s62, s51, s60
	v_lshl_add_u64 v[192:193], s[48:49], 0, v[214:215]
	s_add_i32 m0, s69, 0xc000
	s_nop 0
	global_load_lds_dwordx4 v[192:193], off
	ds_read_b128 v[128:131], v235
	ds_read_b128 v[132:135], v235 offset:1024
	ds_read_b128 v[136:139], v235 offset:2048
	ds_read_b128 v[140:143], v235 offset:3072
	ds_read_b128 v[144:147], v236
	ds_read_b128 v[148:151], v236 offset:1024
	ds_read_b128 v[152:155], v236 offset:2048
	ds_read_b128 v[156:159], v236 offset:3072
	v_lshl_add_u64 v[192:193], s[48:49], 0, v[216:217]
	s_add_i32 m0, s69, 0xe000
	s_nop 0
	global_load_lds_dwordx4 v[192:193], off
	ds_read_b128 v[160:163], v237
	ds_read_b128 v[164:167], v237 offset:1024
	ds_read_b128 v[168:171], v237 offset:2048
	ds_read_b128 v[172:175], v237 offset:3072
	ds_read_b128 v[176:179], v237 offset:4096
	ds_read_b128 v[180:183], v237 offset:5120
	ds_read_b128 v[184:187], v237 offset:6144
	ds_read_b128 v[188:191], v237 offset:7168
	s_waitcnt vmcnt(8)
	s_waitcnt lgkmcnt(0)
	s_setprio 1
	s_barrier
	v_mfma_f32_16x16x32_bf16 v[124:127], v[128:131], v[160:163], v[124:127]
	v_mfma_f32_16x16x32_bf16 v[120:123], v[136:139], v[160:163], v[120:123]
	v_mfma_f32_16x16x32_bf16 v[116:119], v[128:131], v[168:171], v[116:119]
	v_mfma_f32_16x16x32_bf16 v[112:115], v[136:139], v[168:171], v[112:115]
	v_mfma_f32_16x16x32_bf16 v[108:111], v[128:131], v[176:179], v[108:111]
	v_mfma_f32_16x16x32_bf16 v[100:103], v[136:139], v[176:179], v[100:103]
	v_mfma_f32_16x16x32_bf16 v[92:95], v[128:131], v[184:187], v[92:95]
	v_mfma_f32_16x16x32_bf16 v[80:83], v[136:139], v[184:187], v[80:83]
	v_mfma_f32_16x16x32_bf16 v[124:127], v[132:135], v[164:167], v[124:127]
	v_mfma_f32_16x16x32_bf16 v[120:123], v[140:143], v[164:167], v[120:123]
	v_mfma_f32_16x16x32_bf16 v[116:119], v[132:135], v[172:175], v[116:119]
	v_mfma_f32_16x16x32_bf16 v[112:115], v[140:143], v[172:175], v[112:115]
	v_mfma_f32_16x16x32_bf16 v[108:111], v[132:135], v[180:183], v[108:111]
	v_mfma_f32_16x16x32_bf16 v[100:103], v[140:143], v[180:183], v[100:103]
	v_mfma_f32_16x16x32_bf16 v[92:95], v[132:135], v[188:191], v[92:95]
	v_mfma_f32_16x16x32_bf16 v[80:83], v[140:143], v[188:191], v[80:83]
	s_setprio 0
	s_setprio 1
	v_mfma_f32_16x16x32_bf16 v[104:107], v[144:147], v[160:163], v[104:107]
	v_mfma_f32_16x16x32_bf16 v[96:99], v[152:155], v[160:163], v[96:99]
	v_mfma_f32_16x16x32_bf16 v[88:91], v[144:147], v[168:171], v[88:91]
	v_mfma_f32_16x16x32_bf16 v[84:87], v[152:155], v[168:171], v[84:87]
	v_mfma_f32_16x16x32_bf16 v[76:79], v[144:147], v[176:179], v[76:79]
	v_mfma_f32_16x16x32_bf16 v[72:75], v[152:155], v[176:179], v[72:75]
	v_mfma_f32_16x16x32_bf16 v[68:71], v[144:147], v[184:187], v[68:71]
	v_mfma_f32_16x16x32_bf16 v[64:67], v[152:155], v[184:187], v[64:67]
	v_mfma_f32_16x16x32_bf16 v[104:107], v[148:151], v[164:167], v[104:107]
	v_mfma_f32_16x16x32_bf16 v[96:99], v[156:159], v[164:167], v[96:99]
	v_mfma_f32_16x16x32_bf16 v[88:91], v[148:151], v[172:175], v[88:91]
	v_mfma_f32_16x16x32_bf16 v[84:87], v[156:159], v[172:175], v[84:87]
	v_mfma_f32_16x16x32_bf16 v[76:79], v[148:151], v[180:183], v[76:79]
	v_mfma_f32_16x16x32_bf16 v[72:75], v[156:159], v[180:183], v[72:75]
	v_mfma_f32_16x16x32_bf16 v[68:71], v[148:151], v[188:191], v[68:71]
	v_mfma_f32_16x16x32_bf16 v[64:67], v[156:159], v[188:191], v[64:67]
	s_barrier
	s_setprio 0
	s_add_i32 s94, s88, s68
	v_lshl_add_u64 v[192:193], s[62:63], 0, v[208:209]
	s_mov_b32 m0, s94
	s_nop 0
	global_load_lds_dwordx4 v[192:193], off
	ds_read_b128 v[160:163], v237 offset:16384
	ds_read_b128 v[164:167], v237 offset:17408
	s_add_i32 m0, s94, 0x2000
	s_add_u32 s94, s62, 0x40000
	v_lshl_add_u64 v[194:195], s[62:63], 0, v[212:213]
	s_addc_u32 s95, s63, 0
	s_add_i32 s96, s89, s68
	global_load_lds_dwordx4 v[194:195], off
	ds_read_b128 v[168:171], v237 offset:18432
	ds_read_b128 v[172:175], v237 offset:19456
	v_lshl_add_u64 v[196:197], s[94:95], 0, v[208:209]
	s_mov_b32 m0, s96
	v_lshl_add_u64 v[198:199], s[64:65], 0, v[210:211]
	global_load_lds_dwordx4 v[196:197], off
	ds_read_b128 v[176:179], v237 offset:20480
	ds_read_b128 v[180:183], v237 offset:21504
	v_lshl_add_u64 v[196:197], s[94:95], 0, v[212:213]
	s_add_i32 m0, s96, 0x2000
	s_nop 0
	global_load_lds_dwordx4 v[196:197], off
	ds_read_b128 v[184:187], v237 offset:22528
	ds_read_b128 v[188:191], v237 offset:23552
	v_lshl_add_u64 v[196:197], s[64:65], 0, v[206:207]
	s_mov_b32 m0, s69
	s_nop 0
	global_load_lds_dwordx4 v[196:197], off
	s_mov_b32 m0, s70
	s_nop 0
	global_load_lds_dwordx4 v[198:199], off
	s_waitcnt vmcnt(8)
	s_waitcnt lgkmcnt(0)
	s_setprio 1
	s_barrier
	v_mfma_f32_16x16x32_bf16 v[60:63], v[128:131], v[160:163], v[60:63]
	v_mfma_f32_16x16x32_bf16 v[56:59], v[136:139], v[160:163], v[56:59]
	v_mfma_f32_16x16x32_bf16 v[48:51], v[128:131], v[168:171], v[48:51]
	v_mfma_f32_16x16x32_bf16 v[40:43], v[136:139], v[168:171], v[40:43]
	v_mfma_f32_16x16x32_bf16 v[32:35], v[128:131], v[176:179], v[32:35]
	v_mfma_f32_16x16x32_bf16 v[24:27], v[136:139], v[176:179], v[24:27]
	v_mfma_f32_16x16x32_bf16 v[16:19], v[128:131], v[184:187], v[16:19]
	v_mfma_f32_16x16x32_bf16 v[8:11], v[136:139], v[184:187], v[8:11]
	v_mfma_f32_16x16x32_bf16 v[60:63], v[132:135], v[164:167], v[60:63]
	v_mfma_f32_16x16x32_bf16 v[56:59], v[140:143], v[164:167], v[56:59]
	v_mfma_f32_16x16x32_bf16 v[48:51], v[132:135], v[172:175], v[48:51]
	v_mfma_f32_16x16x32_bf16 v[40:43], v[140:143], v[172:175], v[40:43]
	v_mfma_f32_16x16x32_bf16 v[32:35], v[132:135], v[180:183], v[32:35]
	v_mfma_f32_16x16x32_bf16 v[24:27], v[140:143], v[180:183], v[24:27]
	v_mfma_f32_16x16x32_bf16 v[16:19], v[132:135], v[188:191], v[16:19]
	v_mfma_f32_16x16x32_bf16 v[8:11], v[140:143], v[188:191], v[8:11]
	s_setprio 0
	s_setprio 1
	v_mfma_f32_16x16x32_bf16 v[52:55], v[144:147], v[160:163], v[52:55]
	v_mfma_f32_16x16x32_bf16 v[44:47], v[152:155], v[160:163], v[44:47]
	v_mfma_f32_16x16x32_bf16 v[36:39], v[144:147], v[168:171], v[36:39]
	v_mfma_f32_16x16x32_bf16 v[28:31], v[152:155], v[168:171], v[28:31]
	v_mfma_f32_16x16x32_bf16 v[20:23], v[144:147], v[176:179], v[20:23]
	v_mfma_f32_16x16x32_bf16 v[12:15], v[152:155], v[176:179], v[12:15]
	v_mfma_f32_16x16x32_bf16 v[4:7], v[144:147], v[184:187], v[4:7]
	v_mfma_f32_16x16x32_bf16 v[0:3], v[152:155], v[184:187], v[0:3]
	v_mfma_f32_16x16x32_bf16 v[52:55], v[148:151], v[164:167], v[52:55]
	v_mfma_f32_16x16x32_bf16 v[44:47], v[156:159], v[164:167], v[44:47]
	v_mfma_f32_16x16x32_bf16 v[36:39], v[148:151], v[172:175], v[36:39]
	v_mfma_f32_16x16x32_bf16 v[28:31], v[156:159], v[172:175], v[28:31]
	v_mfma_f32_16x16x32_bf16 v[20:23], v[148:151], v[180:183], v[20:23]
	v_mfma_f32_16x16x32_bf16 v[12:15], v[156:159], v[180:183], v[12:15]
	v_mfma_f32_16x16x32_bf16 v[4:7], v[148:151], v[188:191], v[4:7]
	v_mfma_f32_16x16x32_bf16 v[0:3], v[156:159], v[188:191], v[0:3]
	s_barrier
	s_setprio 0
	s_add_i32 s94, 0, 0x18000
	s_add_i32 s95, 0, 0x1c000
	s_add_u32 s64, s64, 0x40000
	s_addc_u32 s65, s65, 0
	s_mov_b32 m0, s71
	v_lshl_add_u64 v[200:201], s[64:65], 0, v[206:207]
	global_load_lds_dwordx4 v[200:201], off
	v_add_u32_e32 v140, s94, v234
	v_add_u32_e32 v156, s95, v234
	ds_read_b128 v[128:131], v140
	ds_read_b128 v[132:135], v140 offset:1024
	ds_read_b128 v[136:139], v140 offset:2048
	ds_read_b128 v[140:143], v140 offset:3072
	ds_read_b128 v[144:147], v156
	ds_read_b128 v[148:151], v156 offset:1024
	ds_read_b128 v[152:155], v156 offset:2048
	ds_read_b128 v[156:159], v156 offset:3072
	v_lshl_add_u64 v[200:201], s[64:65], 0, v[210:211]
	s_mov_b32 m0, s72
	s_nop 0
	global_load_lds_dwordx4 v[200:201], off
	ds_read_b128 v[160:163], v237 offset:32768
	ds_read_b128 v[164:167], v237 offset:33792
	ds_read_b128 v[168:171], v237 offset:34816
	ds_read_b128 v[172:175], v237 offset:35840
	ds_read_b128 v[176:179], v237 offset:36864
	ds_read_b128 v[180:183], v237 offset:37888
	ds_read_b128 v[184:187], v237 offset:38912
	ds_read_b128 v[188:191], v237 offset:39936
	s_waitcnt vmcnt(8)
	s_waitcnt lgkmcnt(0)
	s_setprio 1
	s_barrier
	v_mfma_f32_16x16x32_bf16 v[124:127], v[128:131], v[160:163], v[124:127]
	v_mfma_f32_16x16x32_bf16 v[120:123], v[136:139], v[160:163], v[120:123]
	v_mfma_f32_16x16x32_bf16 v[116:119], v[128:131], v[168:171], v[116:119]
	v_mfma_f32_16x16x32_bf16 v[112:115], v[136:139], v[168:171], v[112:115]
	v_mfma_f32_16x16x32_bf16 v[108:111], v[128:131], v[176:179], v[108:111]
	v_mfma_f32_16x16x32_bf16 v[100:103], v[136:139], v[176:179], v[100:103]
	v_mfma_f32_16x16x32_bf16 v[92:95], v[128:131], v[184:187], v[92:95]
	v_mfma_f32_16x16x32_bf16 v[80:83], v[136:139], v[184:187], v[80:83]
	v_mfma_f32_16x16x32_bf16 v[124:127], v[132:135], v[164:167], v[124:127]
	v_mfma_f32_16x16x32_bf16 v[120:123], v[140:143], v[164:167], v[120:123]
	v_mfma_f32_16x16x32_bf16 v[116:119], v[132:135], v[172:175], v[116:119]
	v_mfma_f32_16x16x32_bf16 v[112:115], v[140:143], v[172:175], v[112:115]
	v_mfma_f32_16x16x32_bf16 v[108:111], v[132:135], v[180:183], v[108:111]
	v_mfma_f32_16x16x32_bf16 v[100:103], v[140:143], v[180:183], v[100:103]
	v_mfma_f32_16x16x32_bf16 v[92:95], v[132:135], v[188:191], v[92:95]
	v_mfma_f32_16x16x32_bf16 v[80:83], v[140:143], v[188:191], v[80:83]
	s_setprio 0
	s_setprio 1
	v_mfma_f32_16x16x32_bf16 v[104:107], v[144:147], v[160:163], v[104:107]
	v_mfma_f32_16x16x32_bf16 v[96:99], v[152:155], v[160:163], v[96:99]
	v_mfma_f32_16x16x32_bf16 v[88:91], v[144:147], v[168:171], v[88:91]
	v_mfma_f32_16x16x32_bf16 v[84:87], v[152:155], v[168:171], v[84:87]
	v_mfma_f32_16x16x32_bf16 v[76:79], v[144:147], v[176:179], v[76:79]
	v_mfma_f32_16x16x32_bf16 v[72:75], v[152:155], v[176:179], v[72:75]
	v_mfma_f32_16x16x32_bf16 v[68:71], v[144:147], v[184:187], v[68:71]
	v_mfma_f32_16x16x32_bf16 v[64:67], v[152:155], v[184:187], v[64:67]
	v_mfma_f32_16x16x32_bf16 v[104:107], v[148:151], v[164:167], v[104:107]
	v_mfma_f32_16x16x32_bf16 v[96:99], v[156:159], v[164:167], v[96:99]
	v_mfma_f32_16x16x32_bf16 v[88:91], v[148:151], v[172:175], v[88:91]
	v_mfma_f32_16x16x32_bf16 v[84:87], v[156:159], v[172:175], v[84:87]
	v_mfma_f32_16x16x32_bf16 v[76:79], v[148:151], v[180:183], v[76:79]
	v_mfma_f32_16x16x32_bf16 v[72:75], v[156:159], v[180:183], v[72:75]
	v_mfma_f32_16x16x32_bf16 v[68:71], v[148:151], v[188:191], v[68:71]
	v_mfma_f32_16x16x32_bf16 v[64:67], v[156:159], v[188:191], v[64:67]
	s_barrier
	s_setprio 0
	s_add_i32 s64, s94, s68
	v_lshl_add_u64 v[192:193], v[192:193], 0, s[14:15]
	s_mov_b32 m0, s64
	s_nop 0
	global_load_lds_dwordx4 v[192:193], off
	ds_read_b128 v[160:163], v237 offset:49152
	ds_read_b128 v[164:167], v237 offset:50176
	s_add_i32 m0, s64, 0x2000
	s_add_u32 s62, s62, 0x40080
	v_lshl_add_u64 v[192:193], v[194:195], 0, s[14:15]
	s_addc_u32 s63, s63, 0
	s_add_i32 s64, s95, s68
	global_load_lds_dwordx4 v[192:193], off
	ds_read_b128 v[168:171], v237 offset:51200
	ds_read_b128 v[172:175], v237 offset:52224
	v_lshl_add_u64 v[192:193], s[62:63], 0, v[208:209]
	s_mov_b32 m0, s64
	s_nop 0
	global_load_lds_dwordx4 v[192:193], off
	ds_read_b128 v[176:179], v237 offset:53248
	ds_read_b128 v[180:183], v237 offset:54272
	v_lshl_add_u64 v[192:193], s[62:63], 0, v[212:213]
	s_add_i32 m0, s64, 0x2000
	s_nop 0
	global_load_lds_dwordx4 v[192:193], off
	ds_read_b128 v[184:187], v237 offset:55296
	ds_read_b128 v[188:191], v237 offset:56320
	v_lshl_add_u64 v[192:193], v[196:197], 0, s[14:15]
	s_mov_b32 m0, s76
	s_nop 0
	global_load_lds_dwordx4 v[192:193], off
	v_lshl_add_u64 v[192:193], v[198:199], 0, s[14:15]
	s_mov_b32 m0, s77
	s_nop 0
	global_load_lds_dwordx4 v[192:193], off
	s_waitcnt vmcnt(8)
	s_waitcnt lgkmcnt(0)
	s_setprio 1
	s_barrier
	v_mfma_f32_16x16x32_bf16 v[60:63], v[128:131], v[160:163], v[60:63]
	v_mfma_f32_16x16x32_bf16 v[56:59], v[136:139], v[160:163], v[56:59]
	v_mfma_f32_16x16x32_bf16 v[48:51], v[128:131], v[168:171], v[48:51]
	v_mfma_f32_16x16x32_bf16 v[40:43], v[136:139], v[168:171], v[40:43]
	v_mfma_f32_16x16x32_bf16 v[32:35], v[128:131], v[176:179], v[32:35]
	v_mfma_f32_16x16x32_bf16 v[24:27], v[136:139], v[176:179], v[24:27]
	v_mfma_f32_16x16x32_bf16 v[16:19], v[128:131], v[184:187], v[16:19]
	v_mfma_f32_16x16x32_bf16 v[8:11], v[136:139], v[184:187], v[8:11]
	v_mfma_f32_16x16x32_bf16 v[60:63], v[132:135], v[164:167], v[60:63]
	v_mfma_f32_16x16x32_bf16 v[56:59], v[140:143], v[164:167], v[56:59]
	v_mfma_f32_16x16x32_bf16 v[48:51], v[132:135], v[172:175], v[48:51]
	v_mfma_f32_16x16x32_bf16 v[40:43], v[140:143], v[172:175], v[40:43]
	v_mfma_f32_16x16x32_bf16 v[32:35], v[132:135], v[180:183], v[32:35]
	v_mfma_f32_16x16x32_bf16 v[24:27], v[140:143], v[180:183], v[24:27]
	v_mfma_f32_16x16x32_bf16 v[16:19], v[132:135], v[188:191], v[16:19]
	v_mfma_f32_16x16x32_bf16 v[8:11], v[140:143], v[188:191], v[8:11]
	s_setprio 0
	s_setprio 1
	v_mfma_f32_16x16x32_bf16 v[52:55], v[144:147], v[160:163], v[52:55]
	v_mfma_f32_16x16x32_bf16 v[44:47], v[152:155], v[160:163], v[44:47]
	v_mfma_f32_16x16x32_bf16 v[36:39], v[144:147], v[168:171], v[36:39]
	v_mfma_f32_16x16x32_bf16 v[28:31], v[152:155], v[168:171], v[28:31]
	v_mfma_f32_16x16x32_bf16 v[20:23], v[144:147], v[176:179], v[20:23]
	v_mfma_f32_16x16x32_bf16 v[12:15], v[152:155], v[176:179], v[12:15]
	v_mfma_f32_16x16x32_bf16 v[4:7], v[144:147], v[184:187], v[4:7]
	v_mfma_f32_16x16x32_bf16 v[0:3], v[152:155], v[184:187], v[0:3]
	v_mfma_f32_16x16x32_bf16 v[52:55], v[148:151], v[164:167], v[52:55]
	v_mfma_f32_16x16x32_bf16 v[44:47], v[156:159], v[164:167], v[44:47]
	v_mfma_f32_16x16x32_bf16 v[36:39], v[148:151], v[172:175], v[36:39]
	v_mfma_f32_16x16x32_bf16 v[28:31], v[156:159], v[172:175], v[28:31]
	v_mfma_f32_16x16x32_bf16 v[20:23], v[148:151], v[180:183], v[20:23]
	v_mfma_f32_16x16x32_bf16 v[12:15], v[156:159], v[180:183], v[12:15]
	v_mfma_f32_16x16x32_bf16 v[4:7], v[148:151], v[188:191], v[4:7]
	v_mfma_f32_16x16x32_bf16 v[0:3], v[156:159], v[188:191], v[0:3]
	s_barrier
	s_setprio 0
	s_add_i32 s93, s93, 2
	s_add_u32 s48, s48, 0x100
	s_addc_u32 s49, s49, 0
	s_add_u32 s60, s60, 0x100
	s_addc_u32 s61, s61, 0
	s_cmp_gt_u32 s93, 13
	s_cbranch_scc0 .LBB0_723
	s_and_b64 vcc, exec, s[16:17]
	s_cbranch_vccz .LBB0_726
	s_barrier

.LBB0_1109:
	s_add_u32 s30, s28, 0xfffc0080
	s_addc_u32 s31, s29, -1
	s_cmp_eq_u32 s64, 12
	s_cselect_b32 s35, s19, s31
	s_cselect_b32 s34, s25, s30
	s_cselect_b32 s31, s17, s63
	s_cselect_b32 s30, s61, s62
	v_lshl_add_u64 v[206:207], s[28:29], 0, v[200:201]
	s_add_i32 m0, s27, 0xc000
	s_nop 0
	global_load_lds_dwordx4 v[206:207], off
	ds_read_b128 v[120:123], v246
	ds_read_b128 v[124:127], v246 offset:1024
	ds_read_b128 v[128:131], v246 offset:2048
	ds_read_b128 v[132:135], v246 offset:3072
	ds_read_b128 v[140:143], v247
	ds_read_b128 v[148:151], v247 offset:1024
	ds_read_b128 v[152:155], v247 offset:2048
	ds_read_b128 v[156:159], v247 offset:3072
	v_lshl_add_u64 v[206:207], s[28:29], 0, v[202:203]
	s_add_i32 m0, s27, 0xe000
	s_nop 0
	global_load_lds_dwordx4 v[206:207], off
	ds_read_b128 v[160:163], v248
	ds_read_b128 v[164:167], v248 offset:1024
	ds_read_b128 v[168:171], v248 offset:2048
	ds_read_b128 v[172:175], v248 offset:3072
	ds_read_b128 v[176:179], v248 offset:4096
	ds_read_b128 v[180:183], v248 offset:5120
	ds_read_b128 v[184:187], v248 offset:6144
	ds_read_b128 v[188:191], v248 offset:7168
	s_waitcnt vmcnt(8)
	s_waitcnt lgkmcnt(0)
	s_setprio 1
	s_barrier
	v_mfma_f32_16x16x32_bf16 v[144:147], v[120:123], v[160:163], v[144:147]
	v_mfma_f32_16x16x32_bf16 v[136:139], v[128:131], v[160:163], v[136:139]
	v_mfma_f32_16x16x32_bf16 v[108:111], v[120:123], v[168:171], v[108:111]
	v_mfma_f32_16x16x32_bf16 v[104:107], v[128:131], v[168:171], v[104:107]
	v_mfma_f32_16x16x32_bf16 v[92:95], v[120:123], v[176:179], v[92:95]
	v_mfma_f32_16x16x32_bf16 v[88:91], v[128:131], v[176:179], v[88:91]
	v_mfma_f32_16x16x32_bf16 v[76:79], v[120:123], v[184:187], v[76:79]
	v_mfma_f32_16x16x32_bf16 v[72:75], v[128:131], v[184:187], v[72:75]
	v_mfma_f32_16x16x32_bf16 v[144:147], v[124:127], v[164:167], v[144:147]
	v_mfma_f32_16x16x32_bf16 v[136:139], v[132:135], v[164:167], v[136:139]
	v_mfma_f32_16x16x32_bf16 v[108:111], v[124:127], v[172:175], v[108:111]
	v_mfma_f32_16x16x32_bf16 v[104:107], v[132:135], v[172:175], v[104:107]
	v_mfma_f32_16x16x32_bf16 v[92:95], v[124:127], v[180:183], v[92:95]
	v_mfma_f32_16x16x32_bf16 v[88:91], v[132:135], v[180:183], v[88:91]
	v_mfma_f32_16x16x32_bf16 v[76:79], v[124:127], v[188:191], v[76:79]
	v_mfma_f32_16x16x32_bf16 v[72:75], v[132:135], v[188:191], v[72:75]
	s_setprio 0
	s_setprio 1
	v_mfma_f32_16x16x32_bf16 v[116:119], v[140:143], v[160:163], v[116:119]
	v_mfma_f32_16x16x32_bf16 v[112:115], v[152:155], v[160:163], v[112:115]
	v_mfma_f32_16x16x32_bf16 v[100:103], v[140:143], v[168:171], v[100:103]
	v_mfma_f32_16x16x32_bf16 v[96:99], v[152:155], v[168:171], v[96:99]
	v_mfma_f32_16x16x32_bf16 v[84:87], v[140:143], v[176:179], v[84:87]
	v_mfma_f32_16x16x32_bf16 v[80:83], v[152:155], v[176:179], v[80:83]
	v_mfma_f32_16x16x32_bf16 v[68:71], v[140:143], v[184:187], v[68:71]
	v_mfma_f32_16x16x32_bf16 v[64:67], v[152:155], v[184:187], v[64:67]
	v_mfma_f32_16x16x32_bf16 v[116:119], v[148:151], v[164:167], v[116:119]
	v_mfma_f32_16x16x32_bf16 v[112:115], v[156:159], v[164:167], v[112:115]
	v_mfma_f32_16x16x32_bf16 v[100:103], v[148:151], v[172:175], v[100:103]
	v_mfma_f32_16x16x32_bf16 v[96:99], v[156:159], v[172:175], v[96:99]
	v_mfma_f32_16x16x32_bf16 v[84:87], v[148:151], v[180:183], v[84:87]
	v_mfma_f32_16x16x32_bf16 v[80:83], v[156:159], v[180:183], v[80:83]
	v_mfma_f32_16x16x32_bf16 v[68:71], v[148:151], v[188:191], v[68:71]
	v_mfma_f32_16x16x32_bf16 v[64:67], v[156:159], v[188:191], v[64:67]
	s_barrier
	s_setprio 0
	s_add_i32 s65, s51, s37
	v_lshl_add_u64 v[206:207], s[30:31], 0, v[194:195]
	s_mov_b32 m0, s65
	s_nop 0
	global_load_lds_dwordx4 v[206:207], off
	ds_read_b128 v[160:163], v248 offset:16384
	ds_read_b128 v[164:167], v248 offset:17408
	s_add_i32 m0, s65, 0x2000
	s_add_u32 s66, s30, 0x40000
	v_lshl_add_u64 v[208:209], s[30:31], 0, v[198:199]
	s_addc_u32 s67, s31, 0
	s_add_i32 s65, s60, s37
	global_load_lds_dwordx4 v[208:209], off
	ds_read_b128 v[168:171], v248 offset:18432
	ds_read_b128 v[172:175], v248 offset:19456
	v_lshl_add_u64 v[210:211], s[66:67], 0, v[194:195]
	s_mov_b32 m0, s65
	v_lshl_add_u64 v[212:213], s[34:35], 0, v[196:197]
	global_load_lds_dwordx4 v[210:211], off
	ds_read_b128 v[176:179], v248 offset:20480
	ds_read_b128 v[180:183], v248 offset:21504
	v_lshl_add_u64 v[210:211], s[66:67], 0, v[198:199]
	s_add_i32 m0, s65, 0x2000
	s_nop 0
	global_load_lds_dwordx4 v[210:211], off
	ds_read_b128 v[184:187], v248 offset:22528
	ds_read_b128 v[188:191], v248 offset:23552
	v_lshl_add_u64 v[210:211], s[34:35], 0, v[192:193]
	s_mov_b32 m0, s27
	s_nop 0
	global_load_lds_dwordx4 v[210:211], off
	s_mov_b32 m0, s38
	s_nop 0
	global_load_lds_dwordx4 v[212:213], off
	s_waitcnt vmcnt(8)
	s_waitcnt lgkmcnt(0)
	s_setprio 1
	s_barrier
	v_mfma_f32_16x16x32_bf16 v[60:63], v[120:123], v[160:163], v[60:63]
	v_mfma_f32_16x16x32_bf16 v[56:59], v[128:131], v[160:163], v[56:59]
	v_mfma_f32_16x16x32_bf16 v[44:47], v[120:123], v[168:171], v[44:47]
	v_mfma_f32_16x16x32_bf16 v[40:43], v[128:131], v[168:171], v[40:43]
	v_mfma_f32_16x16x32_bf16 v[28:31], v[120:123], v[176:179], v[28:31]
	v_mfma_f32_16x16x32_bf16 v[24:27], v[128:131], v[176:179], v[24:27]
	v_mfma_f32_16x16x32_bf16 v[12:15], v[120:123], v[184:187], v[12:15]
	v_mfma_f32_16x16x32_bf16 v[8:11], v[128:131], v[184:187], v[8:11]
	v_mfma_f32_16x16x32_bf16 v[60:63], v[124:127], v[164:167], v[60:63]
	v_mfma_f32_16x16x32_bf16 v[56:59], v[132:135], v[164:167], v[56:59]
	v_mfma_f32_16x16x32_bf16 v[44:47], v[124:127], v[172:175], v[44:47]
	v_mfma_f32_16x16x32_bf16 v[40:43], v[132:135], v[172:175], v[40:43]
	v_mfma_f32_16x16x32_bf16 v[28:31], v[124:127], v[180:183], v[28:31]
	v_mfma_f32_16x16x32_bf16 v[24:27], v[132:135], v[180:183], v[24:27]
	v_mfma_f32_16x16x32_bf16 v[12:15], v[124:127], v[188:191], v[12:15]
	v_mfma_f32_16x16x32_bf16 v[8:11], v[132:135], v[188:191], v[8:11]
	s_setprio 0
	s_setprio 1
	v_mfma_f32_16x16x32_bf16 v[52:55], v[140:143], v[160:163], v[52:55]
	v_mfma_f32_16x16x32_bf16 v[48:51], v[152:155], v[160:163], v[48:51]
	v_mfma_f32_16x16x32_bf16 v[36:39], v[140:143], v[168:171], v[36:39]
	v_mfma_f32_16x16x32_bf16 v[32:35], v[152:155], v[168:171], v[32:35]
	v_mfma_f32_16x16x32_bf16 v[20:23], v[140:143], v[176:179], v[20:23]
	v_mfma_f32_16x16x32_bf16 v[16:19], v[152:155], v[176:179], v[16:19]
	v_mfma_f32_16x16x32_bf16 v[4:7], v[140:143], v[184:187], v[4:7]
	v_mfma_f32_16x16x32_bf16 v[0:3], v[152:155], v[184:187], v[0:3]
	v_mfma_f32_16x16x32_bf16 v[52:55], v[148:151], v[164:167], v[52:55]
	v_mfma_f32_16x16x32_bf16 v[48:51], v[156:159], v[164:167], v[48:51]
	v_mfma_f32_16x16x32_bf16 v[36:39], v[148:151], v[172:175], v[36:39]
	v_mfma_f32_16x16x32_bf16 v[32:35], v[156:159], v[172:175], v[32:35]
	v_mfma_f32_16x16x32_bf16 v[20:23], v[148:151], v[180:183], v[20:23]
	v_mfma_f32_16x16x32_bf16 v[16:19], v[156:159], v[180:183], v[16:19]
	v_mfma_f32_16x16x32_bf16 v[4:7], v[148:151], v[188:191], v[4:7]
	v_mfma_f32_16x16x32_bf16 v[0:3], v[156:159], v[188:191], v[0:3]
	s_barrier
	s_setprio 0
	s_add_i32 s65, 0, 0x18000
	s_add_i32 s66, 0, 0x1c000
	s_add_u32 s34, s34, 0x40000
	s_addc_u32 s35, s35, 0
	s_mov_b32 m0, s39
	v_lshl_add_u64 v[214:215], s[34:35], 0, v[192:193]
	global_load_lds_dwordx4 v[214:215], off
	v_add_u32_e32 v132, s65, v245
	v_add_u32_e32 v156, s66, v245
	ds_read_b128 v[120:123], v132
	ds_read_b128 v[124:127], v132 offset:1024
	ds_read_b128 v[128:131], v132 offset:2048
	ds_read_b128 v[132:135], v132 offset:3072
	ds_read_b128 v[140:143], v156
	ds_read_b128 v[148:151], v156 offset:1024
	ds_read_b128 v[152:155], v156 offset:2048
	ds_read_b128 v[156:159], v156 offset:3072
	v_lshl_add_u64 v[214:215], s[34:35], 0, v[196:197]
	s_mov_b32 m0, s40
	s_nop 0
	global_load_lds_dwordx4 v[214:215], off
	ds_read_b128 v[160:163], v248 offset:32768
	ds_read_b128 v[164:167], v248 offset:33792
	ds_read_b128 v[168:171], v248 offset:34816
	ds_read_b128 v[172:175], v248 offset:35840
	ds_read_b128 v[176:179], v248 offset:36864
	ds_read_b128 v[180:183], v248 offset:37888
	ds_read_b128 v[184:187], v248 offset:38912
	ds_read_b128 v[188:191], v248 offset:39936
	s_waitcnt vmcnt(8)
	s_waitcnt lgkmcnt(0)
	s_setprio 1
	s_barrier
	v_mfma_f32_16x16x32_bf16 v[144:147], v[120:123], v[160:163], v[144:147]
	v_mfma_f32_16x16x32_bf16 v[136:139], v[128:131], v[160:163], v[136:139]
	v_mfma_f32_16x16x32_bf16 v[108:111], v[120:123], v[168:171], v[108:111]
	v_mfma_f32_16x16x32_bf16 v[104:107], v[128:131], v[168:171], v[104:107]
	v_mfma_f32_16x16x32_bf16 v[92:95], v[120:123], v[176:179], v[92:95]
	v_mfma_f32_16x16x32_bf16 v[88:91], v[128:131], v[176:179], v[88:91]
	v_mfma_f32_16x16x32_bf16 v[76:79], v[120:123], v[184:187], v[76:79]
	v_mfma_f32_16x16x32_bf16 v[72:75], v[128:131], v[184:187], v[72:75]
	v_mfma_f32_16x16x32_bf16 v[144:147], v[124:127], v[164:167], v[144:147]
	v_mfma_f32_16x16x32_bf16 v[136:139], v[132:135], v[164:167], v[136:139]
	v_mfma_f32_16x16x32_bf16 v[108:111], v[124:127], v[172:175], v[108:111]
	v_mfma_f32_16x16x32_bf16 v[104:107], v[132:135], v[172:175], v[104:107]
	v_mfma_f32_16x16x32_bf16 v[92:95], v[124:127], v[180:183], v[92:95]
	v_mfma_f32_16x16x32_bf16 v[88:91], v[132:135], v[180:183], v[88:91]
	v_mfma_f32_16x16x32_bf16 v[76:79], v[124:127], v[188:191], v[76:79]
	v_mfma_f32_16x16x32_bf16 v[72:75], v[132:135], v[188:191], v[72:75]
	s_setprio 0
	s_setprio 1
	v_mfma_f32_16x16x32_bf16 v[116:119], v[140:143], v[160:163], v[116:119]
	v_mfma_f32_16x16x32_bf16 v[112:115], v[152:155], v[160:163], v[112:115]
	v_mfma_f32_16x16x32_bf16 v[100:103], v[140:143], v[168:171], v[100:103]
	v_mfma_f32_16x16x32_bf16 v[96:99], v[152:155], v[168:171], v[96:99]
	v_mfma_f32_16x16x32_bf16 v[84:87], v[140:143], v[176:179], v[84:87]
	v_mfma_f32_16x16x32_bf16 v[80:83], v[152:155], v[176:179], v[80:83]
	v_mfma_f32_16x16x32_bf16 v[68:71], v[140:143], v[184:187], v[68:71]
	v_mfma_f32_16x16x32_bf16 v[64:67], v[152:155], v[184:187], v[64:67]
	v_mfma_f32_16x16x32_bf16 v[116:119], v[148:151], v[164:167], v[116:119]
	v_mfma_f32_16x16x32_bf16 v[112:115], v[156:159], v[164:167], v[112:115]
	v_mfma_f32_16x16x32_bf16 v[100:103], v[148:151], v[172:175], v[100:103]
	v_mfma_f32_16x16x32_bf16 v[96:99], v[156:159], v[172:175], v[96:99]
	v_mfma_f32_16x16x32_bf16 v[84:87], v[148:151], v[180:183], v[84:87]
	v_mfma_f32_16x16x32_bf16 v[80:83], v[156:159], v[180:183], v[80:83]
	v_mfma_f32_16x16x32_bf16 v[68:71], v[148:151], v[188:191], v[68:71]
	v_mfma_f32_16x16x32_bf16 v[64:67], v[156:159], v[188:191], v[64:67]
	s_barrier
	s_setprio 0
	s_add_i32 s34, s65, s37
	v_lshl_add_u64 v[206:207], v[206:207], 0, s[12:13]
	s_mov_b32 m0, s34
	s_nop 0
	global_load_lds_dwordx4 v[206:207], off
	ds_read_b128 v[160:163], v248 offset:49152
	ds_read_b128 v[164:167], v248 offset:50176
	s_add_i32 m0, s34, 0x2000
	s_add_u32 s30, s30, 0x40080
	v_lshl_add_u64 v[206:207], v[208:209], 0, s[12:13]
	s_addc_u32 s31, s31, 0
	s_add_i32 s34, s66, s37
	global_load_lds_dwordx4 v[206:207], off
	ds_read_b128 v[168:171], v248 offset:51200
	ds_read_b128 v[172:175], v248 offset:52224
	v_lshl_add_u64 v[206:207], s[30:31], 0, v[194:195]
	s_mov_b32 m0, s34
	s_nop 0
	global_load_lds_dwordx4 v[206:207], off
	ds_read_b128 v[176:179], v248 offset:53248
	ds_read_b128 v[180:183], v248 offset:54272
	v_lshl_add_u64 v[206:207], s[30:31], 0, v[198:199]
	s_add_i32 m0, s34, 0x2000
	s_nop 0
	global_load_lds_dwordx4 v[206:207], off
	ds_read_b128 v[184:187], v248 offset:55296
	ds_read_b128 v[188:191], v248 offset:56320
	v_lshl_add_u64 v[206:207], v[210:211], 0, s[12:13]
	s_mov_b32 m0, s46
	s_nop 0
	global_load_lds_dwordx4 v[206:207], off
	v_lshl_add_u64 v[206:207], v[212:213], 0, s[12:13]
	s_mov_b32 m0, s47
	s_nop 0
	global_load_lds_dwordx4 v[206:207], off
	s_waitcnt vmcnt(8)
	s_waitcnt lgkmcnt(0)
	s_setprio 1
	s_barrier
	v_mfma_f32_16x16x32_bf16 v[60:63], v[120:123], v[160:163], v[60:63]
	v_mfma_f32_16x16x32_bf16 v[56:59], v[128:131], v[160:163], v[56:59]
	v_mfma_f32_16x16x32_bf16 v[44:47], v[120:123], v[168:171], v[44:47]
	v_mfma_f32_16x16x32_bf16 v[40:43], v[128:131], v[168:171], v[40:43]
	v_mfma_f32_16x16x32_bf16 v[28:31], v[120:123], v[176:179], v[28:31]
	v_mfma_f32_16x16x32_bf16 v[24:27], v[128:131], v[176:179], v[24:27]
	v_mfma_f32_16x16x32_bf16 v[12:15], v[120:123], v[184:187], v[12:15]
	v_mfma_f32_16x16x32_bf16 v[8:11], v[128:131], v[184:187], v[8:11]
	v_mfma_f32_16x16x32_bf16 v[60:63], v[124:127], v[164:167], v[60:63]
	v_mfma_f32_16x16x32_bf16 v[56:59], v[132:135], v[164:167], v[56:59]
	v_mfma_f32_16x16x32_bf16 v[44:47], v[124:127], v[172:175], v[44:47]
	v_mfma_f32_16x16x32_bf16 v[40:43], v[132:135], v[172:175], v[40:43]
	v_mfma_f32_16x16x32_bf16 v[28:31], v[124:127], v[180:183], v[28:31]
	v_mfma_f32_16x16x32_bf16 v[24:27], v[132:135], v[180:183], v[24:27]
	v_mfma_f32_16x16x32_bf16 v[12:15], v[124:127], v[188:191], v[12:15]
	v_mfma_f32_16x16x32_bf16 v[8:11], v[132:135], v[188:191], v[8:11]
	s_setprio 0
	s_setprio 1
	v_mfma_f32_16x16x32_bf16 v[52:55], v[140:143], v[160:163], v[52:55]
	v_mfma_f32_16x16x32_bf16 v[48:51], v[152:155], v[160:163], v[48:51]
	v_mfma_f32_16x16x32_bf16 v[36:39], v[140:143], v[168:171], v[36:39]
	v_mfma_f32_16x16x32_bf16 v[32:35], v[152:155], v[168:171], v[32:35]
	v_mfma_f32_16x16x32_bf16 v[20:23], v[140:143], v[176:179], v[20:23]
	v_mfma_f32_16x16x32_bf16 v[16:19], v[152:155], v[176:179], v[16:19]
	v_mfma_f32_16x16x32_bf16 v[4:7], v[140:143], v[184:187], v[4:7]
	v_mfma_f32_16x16x32_bf16 v[0:3], v[152:155], v[184:187], v[0:3]
	v_mfma_f32_16x16x32_bf16 v[52:55], v[148:151], v[164:167], v[52:55]
	v_mfma_f32_16x16x32_bf16 v[48:51], v[156:159], v[164:167], v[48:51]
	v_mfma_f32_16x16x32_bf16 v[36:39], v[148:151], v[172:175], v[36:39]
	v_mfma_f32_16x16x32_bf16 v[32:35], v[156:159], v[172:175], v[32:35]
	v_mfma_f32_16x16x32_bf16 v[20:23], v[148:151], v[180:183], v[20:23]
	v_mfma_f32_16x16x32_bf16 v[16:19], v[156:159], v[180:183], v[16:19]
	v_mfma_f32_16x16x32_bf16 v[4:7], v[148:151], v[188:191], v[4:7]
	v_mfma_f32_16x16x32_bf16 v[0:3], v[156:159], v[188:191], v[0:3]
	s_barrier
	s_setprio 0
	s_add_i32 s64, s64, 2
	s_add_u32 s28, s28, 0x100
	s_addc_u32 s29, s29, 0
	s_add_u32 s62, s62, 0x100
	s_addc_u32 s63, s63, 0
	s_cmp_gt_u32 s64, 13
	s_cbranch_scc0 .LBB0_1109
	s_and_b64 vcc, exec, s[14:15]
	s_cbranch_vccz .LBB0_1112
	s_barrier

.LBB0_1193:
	s_add_u32 s30, s28, 0xfffc0080
	s_addc_u32 s31, s29, -1
	s_cmp_eq_u32 s62, 12
	s_cselect_b32 s35, s19, s31
	s_cselect_b32 s34, s50, s30
	s_cselect_b32 s31, s17, s61
	s_cselect_b32 s30, s51, s60
	v_lshl_add_u64 v[144:145], s[28:29], 0, v[136:137]
	s_add_i32 m0, s25, 0xc000
	s_nop 0
	global_load_lds_dwordx4 v[144:145], off
	ds_read_b128 v[154:157], v149
	ds_read_b128 v[158:161], v149 offset:1024
	ds_read_b128 v[162:165], v149 offset:2048
	ds_read_b128 v[166:169], v149 offset:3072
	ds_read_b128 v[170:173], v150
	ds_read_b128 v[174:177], v150 offset:1024
	ds_read_b128 v[178:181], v150 offset:2048
	ds_read_b128 v[182:185], v150 offset:3072
	v_lshl_add_u64 v[144:145], s[28:29], 0, v[138:139]
	s_add_i32 m0, s25, 0xe000
	s_nop 0
	global_load_lds_dwordx4 v[144:145], off
	ds_read_b128 v[186:189], v151
	ds_read_b128 v[190:193], v151 offset:1024
	ds_read_b128 v[194:197], v151 offset:2048
	ds_read_b128 v[198:201], v151 offset:3072
	ds_read_b128 v[202:205], v151 offset:4096
	ds_read_b128 v[206:209], v151 offset:5120
	ds_read_b128 v[210:213], v151 offset:6144
	ds_read_b128 v[214:217], v151 offset:7168
	s_waitcnt vmcnt(8)
	s_waitcnt lgkmcnt(0)
	s_setprio 1
	s_barrier
	v_mfma_f32_16x16x32_bf16 v[116:119], v[154:157], v[186:189], v[116:119]
	v_mfma_f32_16x16x32_bf16 v[112:115], v[162:165], v[186:189], v[112:115]
	v_mfma_f32_16x16x32_bf16 v[108:111], v[154:157], v[194:197], v[108:111]
	v_mfma_f32_16x16x32_bf16 v[100:103], v[162:165], v[194:197], v[100:103]
	v_mfma_f32_16x16x32_bf16 v[92:95], v[154:157], v[202:205], v[92:95]
	v_mfma_f32_16x16x32_bf16 v[84:87], v[162:165], v[202:205], v[84:87]
	v_mfma_f32_16x16x32_bf16 v[76:79], v[154:157], v[210:213], v[76:79]
	v_mfma_f32_16x16x32_bf16 v[68:71], v[162:165], v[210:213], v[68:71]
	v_mfma_f32_16x16x32_bf16 v[116:119], v[158:161], v[190:193], v[116:119]
	v_mfma_f32_16x16x32_bf16 v[112:115], v[166:169], v[190:193], v[112:115]
	v_mfma_f32_16x16x32_bf16 v[108:111], v[158:161], v[198:201], v[108:111]
	v_mfma_f32_16x16x32_bf16 v[100:103], v[166:169], v[198:201], v[100:103]
	v_mfma_f32_16x16x32_bf16 v[92:95], v[158:161], v[206:209], v[92:95]
	v_mfma_f32_16x16x32_bf16 v[84:87], v[166:169], v[206:209], v[84:87]
	v_mfma_f32_16x16x32_bf16 v[76:79], v[158:161], v[214:217], v[76:79]
	v_mfma_f32_16x16x32_bf16 v[68:71], v[166:169], v[214:217], v[68:71]
	s_setprio 0
	s_setprio 1
	v_mfma_f32_16x16x32_bf16 v[124:127], v[170:173], v[186:189], v[124:127]
	v_mfma_f32_16x16x32_bf16 v[120:123], v[178:181], v[186:189], v[120:123]
	v_mfma_f32_16x16x32_bf16 v[104:107], v[170:173], v[194:197], v[104:107]
	v_mfma_f32_16x16x32_bf16 v[96:99], v[178:181], v[194:197], v[96:99]
	v_mfma_f32_16x16x32_bf16 v[88:91], v[170:173], v[202:205], v[88:91]
	v_mfma_f32_16x16x32_bf16 v[80:83], v[178:181], v[202:205], v[80:83]
	v_mfma_f32_16x16x32_bf16 v[72:75], v[170:173], v[210:213], v[72:75]
	v_mfma_f32_16x16x32_bf16 v[64:67], v[178:181], v[210:213], v[64:67]
	v_mfma_f32_16x16x32_bf16 v[124:127], v[174:177], v[190:193], v[124:127]
	v_mfma_f32_16x16x32_bf16 v[120:123], v[182:185], v[190:193], v[120:123]
	v_mfma_f32_16x16x32_bf16 v[104:107], v[174:177], v[198:201], v[104:107]
	v_mfma_f32_16x16x32_bf16 v[96:99], v[182:185], v[198:201], v[96:99]
	v_mfma_f32_16x16x32_bf16 v[88:91], v[174:177], v[206:209], v[88:91]
	v_mfma_f32_16x16x32_bf16 v[80:83], v[182:185], v[206:209], v[80:83]
	v_mfma_f32_16x16x32_bf16 v[72:75], v[174:177], v[214:217], v[72:75]
	v_mfma_f32_16x16x32_bf16 v[64:67], v[182:185], v[214:217], v[64:67]
	s_barrier
	s_setprio 0
	s_add_i32 s63, s47, s5
	v_lshl_add_u64 v[144:145], s[30:31], 0, v[132:133]
	s_mov_b32 m0, s63
	s_nop 0
	global_load_lds_dwordx4 v[144:145], off
	ds_read_b128 v[186:189], v151 offset:16384
	ds_read_b128 v[190:193], v151 offset:17408
	s_add_i32 m0, s63, 0x2000
	s_add_u32 s64, s30, 0x40000
	v_lshl_add_u64 v[218:219], s[30:31], 0, v[128:129]
	s_addc_u32 s65, s31, 0
	s_add_i32 s63, s48, s5
	global_load_lds_dwordx4 v[218:219], off
	ds_read_b128 v[194:197], v151 offset:18432
	ds_read_b128 v[198:201], v151 offset:19456
	v_lshl_add_u64 v[220:221], s[64:65], 0, v[132:133]
	s_mov_b32 m0, s63
	v_lshl_add_u64 v[222:223], s[34:35], 0, v[130:131]
	global_load_lds_dwordx4 v[220:221], off
	ds_read_b128 v[202:205], v151 offset:20480
	ds_read_b128 v[206:209], v151 offset:21504
	v_lshl_add_u64 v[220:221], s[64:65], 0, v[128:129]
	s_add_i32 m0, s63, 0x2000
	s_nop 0
	global_load_lds_dwordx4 v[220:221], off
	ds_read_b128 v[210:213], v151 offset:22528
	ds_read_b128 v[214:217], v151 offset:23552
	v_lshl_add_u64 v[220:221], s[34:35], 0, v[134:135]
	s_mov_b32 m0, s25
	s_nop 0
	global_load_lds_dwordx4 v[220:221], off
	s_mov_b32 m0, s27
	s_nop 0
	global_load_lds_dwordx4 v[222:223], off
	s_waitcnt vmcnt(8)
	s_waitcnt lgkmcnt(0)
	s_setprio 1
	s_barrier
	v_mfma_f32_16x16x32_bf16 v[60:63], v[154:157], v[186:189], v[60:63]
	v_mfma_f32_16x16x32_bf16 v[52:55], v[162:165], v[186:189], v[52:55]
	v_mfma_f32_16x16x32_bf16 v[44:47], v[154:157], v[194:197], v[44:47]
	v_mfma_f32_16x16x32_bf16 v[36:39], v[162:165], v[194:197], v[36:39]
	v_mfma_f32_16x16x32_bf16 v[28:31], v[154:157], v[202:205], v[28:31]
	v_mfma_f32_16x16x32_bf16 v[20:23], v[162:165], v[202:205], v[20:23]
	v_mfma_f32_16x16x32_bf16 v[12:15], v[154:157], v[210:213], v[12:15]
	v_mfma_f32_16x16x32_bf16 v[4:7], v[162:165], v[210:213], v[4:7]
	v_mfma_f32_16x16x32_bf16 v[60:63], v[158:161], v[190:193], v[60:63]
	v_mfma_f32_16x16x32_bf16 v[52:55], v[166:169], v[190:193], v[52:55]
	v_mfma_f32_16x16x32_bf16 v[44:47], v[158:161], v[198:201], v[44:47]
	v_mfma_f32_16x16x32_bf16 v[36:39], v[166:169], v[198:201], v[36:39]
	v_mfma_f32_16x16x32_bf16 v[28:31], v[158:161], v[206:209], v[28:31]
	v_mfma_f32_16x16x32_bf16 v[20:23], v[166:169], v[206:209], v[20:23]
	v_mfma_f32_16x16x32_bf16 v[12:15], v[158:161], v[214:217], v[12:15]
	v_mfma_f32_16x16x32_bf16 v[4:7], v[166:169], v[214:217], v[4:7]
	s_setprio 0
	s_setprio 1
	v_mfma_f32_16x16x32_bf16 v[56:59], v[170:173], v[186:189], v[56:59]
	v_mfma_f32_16x16x32_bf16 v[48:51], v[178:181], v[186:189], v[48:51]
	v_mfma_f32_16x16x32_bf16 v[40:43], v[170:173], v[194:197], v[40:43]
	v_mfma_f32_16x16x32_bf16 v[32:35], v[178:181], v[194:197], v[32:35]
	v_mfma_f32_16x16x32_bf16 v[24:27], v[170:173], v[202:205], v[24:27]
	v_mfma_f32_16x16x32_bf16 v[16:19], v[178:181], v[202:205], v[16:19]
	v_mfma_f32_16x16x32_bf16 v[8:11], v[170:173], v[210:213], v[8:11]
	v_mfma_f32_16x16x32_bf16 v[0:3], v[178:181], v[210:213], v[0:3]
	v_mfma_f32_16x16x32_bf16 v[56:59], v[174:177], v[190:193], v[56:59]
	v_mfma_f32_16x16x32_bf16 v[48:51], v[182:185], v[190:193], v[48:51]
	v_mfma_f32_16x16x32_bf16 v[40:43], v[174:177], v[198:201], v[40:43]
	v_mfma_f32_16x16x32_bf16 v[32:35], v[182:185], v[198:201], v[32:35]
	v_mfma_f32_16x16x32_bf16 v[24:27], v[174:177], v[206:209], v[24:27]
	v_mfma_f32_16x16x32_bf16 v[16:19], v[182:185], v[206:209], v[16:19]
	v_mfma_f32_16x16x32_bf16 v[8:11], v[174:177], v[214:217], v[8:11]
	v_mfma_f32_16x16x32_bf16 v[0:3], v[182:185], v[214:217], v[0:3]
	s_barrier
	s_setprio 0
	s_add_i32 s63, 0, 0x18000
	s_add_i32 s64, 0, 0x1c000
	s_add_u32 s34, s34, 0x40000
	s_addc_u32 s35, s35, 0
	s_mov_b32 m0, s38
	v_lshl_add_u64 v[224:225], s[34:35], 0, v[134:135]
	global_load_lds_dwordx4 v[224:225], off
	v_add_u32_e32 v153, s63, v147
	ds_read_b128 v[154:157], v153
	ds_read_b128 v[158:161], v153 offset:1024
	ds_read_b128 v[162:165], v153 offset:2048
	ds_read_b128 v[166:169], v153 offset:3072
	v_add_u32_e32 v153, s64, v147
	ds_read_b128 v[170:173], v153
	ds_read_b128 v[174:177], v153 offset:1024
	ds_read_b128 v[178:181], v153 offset:2048
	ds_read_b128 v[182:185], v153 offset:3072
	v_lshl_add_u64 v[224:225], s[34:35], 0, v[130:131]
	s_mov_b32 m0, s39
	s_nop 0
	global_load_lds_dwordx4 v[224:225], off
	ds_read_b128 v[186:189], v151 offset:32768
	ds_read_b128 v[190:193], v151 offset:33792
	ds_read_b128 v[194:197], v151 offset:34816
	ds_read_b128 v[198:201], v151 offset:35840
	ds_read_b128 v[202:205], v151 offset:36864
	ds_read_b128 v[206:209], v151 offset:37888
	ds_read_b128 v[210:213], v151 offset:38912
	ds_read_b128 v[214:217], v151 offset:39936
	s_waitcnt vmcnt(8)
	s_waitcnt lgkmcnt(0)
	s_setprio 1
	s_barrier
	v_mfma_f32_16x16x32_bf16 v[116:119], v[154:157], v[186:189], v[116:119]
	v_mfma_f32_16x16x32_bf16 v[112:115], v[162:165], v[186:189], v[112:115]
	v_mfma_f32_16x16x32_bf16 v[108:111], v[154:157], v[194:197], v[108:111]
	v_mfma_f32_16x16x32_bf16 v[100:103], v[162:165], v[194:197], v[100:103]
	v_mfma_f32_16x16x32_bf16 v[92:95], v[154:157], v[202:205], v[92:95]
	v_mfma_f32_16x16x32_bf16 v[84:87], v[162:165], v[202:205], v[84:87]
	v_mfma_f32_16x16x32_bf16 v[76:79], v[154:157], v[210:213], v[76:79]
	v_mfma_f32_16x16x32_bf16 v[68:71], v[162:165], v[210:213], v[68:71]
	v_mfma_f32_16x16x32_bf16 v[116:119], v[158:161], v[190:193], v[116:119]
	v_mfma_f32_16x16x32_bf16 v[112:115], v[166:169], v[190:193], v[112:115]
	v_mfma_f32_16x16x32_bf16 v[108:111], v[158:161], v[198:201], v[108:111]
	v_mfma_f32_16x16x32_bf16 v[100:103], v[166:169], v[198:201], v[100:103]
	v_mfma_f32_16x16x32_bf16 v[92:95], v[158:161], v[206:209], v[92:95]
	v_mfma_f32_16x16x32_bf16 v[84:87], v[166:169], v[206:209], v[84:87]
	v_mfma_f32_16x16x32_bf16 v[76:79], v[158:161], v[214:217], v[76:79]
	v_mfma_f32_16x16x32_bf16 v[68:71], v[166:169], v[214:217], v[68:71]
	s_setprio 0
	s_setprio 1
	v_mfma_f32_16x16x32_bf16 v[124:127], v[170:173], v[186:189], v[124:127]
	v_mfma_f32_16x16x32_bf16 v[120:123], v[178:181], v[186:189], v[120:123]
	v_mfma_f32_16x16x32_bf16 v[104:107], v[170:173], v[194:197], v[104:107]
	v_mfma_f32_16x16x32_bf16 v[96:99], v[178:181], v[194:197], v[96:99]
	v_mfma_f32_16x16x32_bf16 v[88:91], v[170:173], v[202:205], v[88:91]
	v_mfma_f32_16x16x32_bf16 v[80:83], v[178:181], v[202:205], v[80:83]
	v_mfma_f32_16x16x32_bf16 v[72:75], v[170:173], v[210:213], v[72:75]
	v_mfma_f32_16x16x32_bf16 v[64:67], v[178:181], v[210:213], v[64:67]
	v_mfma_f32_16x16x32_bf16 v[124:127], v[174:177], v[190:193], v[124:127]
	v_mfma_f32_16x16x32_bf16 v[120:123], v[182:185], v[190:193], v[120:123]
	v_mfma_f32_16x16x32_bf16 v[104:107], v[174:177], v[198:201], v[104:107]
	v_mfma_f32_16x16x32_bf16 v[96:99], v[182:185], v[198:201], v[96:99]
	v_mfma_f32_16x16x32_bf16 v[88:91], v[174:177], v[206:209], v[88:91]
	v_mfma_f32_16x16x32_bf16 v[80:83], v[182:185], v[206:209], v[80:83]
	v_mfma_f32_16x16x32_bf16 v[72:75], v[174:177], v[214:217], v[72:75]
	v_mfma_f32_16x16x32_bf16 v[64:67], v[182:185], v[214:217], v[64:67]
	s_barrier
	s_setprio 0
	s_add_i32 s34, s63, s5
	v_lshl_add_u64 v[144:145], v[144:145], 0, s[12:13]
	s_mov_b32 m0, s34
	s_nop 0
	global_load_lds_dwordx4 v[144:145], off
	ds_read_b128 v[186:189], v151 offset:49152
	ds_read_b128 v[190:193], v151 offset:50176
	s_add_i32 m0, s34, 0x2000
	s_add_u32 s30, s30, 0x40080
	v_lshl_add_u64 v[144:145], v[218:219], 0, s[12:13]
	s_addc_u32 s31, s31, 0
	s_add_i32 s34, s64, s5
	global_load_lds_dwordx4 v[144:145], off
	ds_read_b128 v[194:197], v151 offset:51200
	ds_read_b128 v[198:201], v151 offset:52224
	v_lshl_add_u64 v[144:145], s[30:31], 0, v[132:133]
	s_mov_b32 m0, s34
	s_nop 0
	global_load_lds_dwordx4 v[144:145], off
	ds_read_b128 v[202:205], v151 offset:53248
	ds_read_b128 v[206:209], v151 offset:54272
	v_lshl_add_u64 v[144:145], s[30:31], 0, v[128:129]
	s_add_i32 m0, s34, 0x2000
	s_nop 0
	global_load_lds_dwordx4 v[144:145], off
	ds_read_b128 v[210:213], v151 offset:55296
	ds_read_b128 v[214:217], v151 offset:56320
	v_lshl_add_u64 v[144:145], v[220:221], 0, s[12:13]
	s_mov_b32 m0, s41
	s_nop 0
	global_load_lds_dwordx4 v[144:145], off
	v_lshl_add_u64 v[144:145], v[222:223], 0, s[12:13]
	s_mov_b32 m0, s42
	s_nop 0
	global_load_lds_dwordx4 v[144:145], off
	s_waitcnt vmcnt(8)
	s_waitcnt lgkmcnt(0)
	s_setprio 1
	s_barrier
	v_mfma_f32_16x16x32_bf16 v[60:63], v[154:157], v[186:189], v[60:63]
	v_mfma_f32_16x16x32_bf16 v[52:55], v[162:165], v[186:189], v[52:55]
	v_mfma_f32_16x16x32_bf16 v[44:47], v[154:157], v[194:197], v[44:47]
	v_mfma_f32_16x16x32_bf16 v[36:39], v[162:165], v[194:197], v[36:39]
	v_mfma_f32_16x16x32_bf16 v[28:31], v[154:157], v[202:205], v[28:31]
	v_mfma_f32_16x16x32_bf16 v[20:23], v[162:165], v[202:205], v[20:23]
	v_mfma_f32_16x16x32_bf16 v[12:15], v[154:157], v[210:213], v[12:15]
	v_mfma_f32_16x16x32_bf16 v[4:7], v[162:165], v[210:213], v[4:7]
	v_mfma_f32_16x16x32_bf16 v[60:63], v[158:161], v[190:193], v[60:63]
	v_mfma_f32_16x16x32_bf16 v[52:55], v[166:169], v[190:193], v[52:55]
	v_mfma_f32_16x16x32_bf16 v[44:47], v[158:161], v[198:201], v[44:47]
	v_mfma_f32_16x16x32_bf16 v[36:39], v[166:169], v[198:201], v[36:39]
	v_mfma_f32_16x16x32_bf16 v[28:31], v[158:161], v[206:209], v[28:31]
	v_mfma_f32_16x16x32_bf16 v[20:23], v[166:169], v[206:209], v[20:23]
	v_mfma_f32_16x16x32_bf16 v[12:15], v[158:161], v[214:217], v[12:15]
	v_mfma_f32_16x16x32_bf16 v[4:7], v[166:169], v[214:217], v[4:7]
	s_setprio 0
	s_setprio 1
	v_mfma_f32_16x16x32_bf16 v[56:59], v[170:173], v[186:189], v[56:59]
	v_mfma_f32_16x16x32_bf16 v[48:51], v[178:181], v[186:189], v[48:51]
	v_mfma_f32_16x16x32_bf16 v[40:43], v[170:173], v[194:197], v[40:43]
	v_mfma_f32_16x16x32_bf16 v[32:35], v[178:181], v[194:197], v[32:35]
	v_mfma_f32_16x16x32_bf16 v[24:27], v[170:173], v[202:205], v[24:27]
	v_mfma_f32_16x16x32_bf16 v[16:19], v[178:181], v[202:205], v[16:19]
	v_mfma_f32_16x16x32_bf16 v[8:11], v[170:173], v[210:213], v[8:11]
	v_mfma_f32_16x16x32_bf16 v[0:3], v[178:181], v[210:213], v[0:3]
	v_mfma_f32_16x16x32_bf16 v[56:59], v[174:177], v[190:193], v[56:59]
	v_mfma_f32_16x16x32_bf16 v[48:51], v[182:185], v[190:193], v[48:51]
	v_mfma_f32_16x16x32_bf16 v[40:43], v[174:177], v[198:201], v[40:43]
	v_mfma_f32_16x16x32_bf16 v[32:35], v[182:185], v[198:201], v[32:35]
	v_mfma_f32_16x16x32_bf16 v[24:27], v[174:177], v[206:209], v[24:27]
	v_mfma_f32_16x16x32_bf16 v[16:19], v[182:185], v[206:209], v[16:19]
	v_mfma_f32_16x16x32_bf16 v[8:11], v[174:177], v[214:217], v[8:11]
	v_mfma_f32_16x16x32_bf16 v[0:3], v[182:185], v[214:217], v[0:3]
	s_barrier
	s_setprio 0
	s_add_i32 s62, s62, 2
	s_add_u32 s28, s28, 0x100
	s_addc_u32 s29, s29, 0
	s_add_u32 s60, s60, 0x100
	s_addc_u32 s61, s61, 0
	s_cmp_gt_u32 s62, 13
	s_cbranch_scc0 .LBB0_1193
	s_and_b64 vcc, exec, s[14:15]
	s_cbranch_vccz .LBB0_1196
	s_barrier

.LBB0_1273:
	s_add_u32 s18, s16, 0x100
	s_addc_u32 s19, s17, 0
	s_cmp_eq_u32 s46, 40
	s_cselect_b32 s23, s5, s19
	s_cselect_b32 s22, s4, s18
	s_cselect_b32 s21, s15, s45
	s_cselect_b32 s20, s14, s44
	v_lshl_add_u64 v[192:193], s[16:17], 0, v[172:173]
	s_add_i32 m0, s26, 0xc000
	s_nop 0
	global_load_lds_dwordx4 v[192:193], off
	ds_read_b128 v[128:131], v197
	ds_read_b128 v[132:135], v197 offset:1024
	ds_read_b128 v[136:139], v197 offset:2048
	ds_read_b128 v[140:143], v197 offset:3072
	ds_read_b128 v[144:147], v198
	ds_read_b128 v[148:151], v198 offset:1024
	ds_read_b128 v[152:155], v198 offset:2048
	ds_read_b128 v[156:159], v198 offset:3072
	v_lshl_add_u64 v[192:193], s[16:17], 0, v[174:175]
	s_add_i32 m0, s26, 0xe000
	s_nop 0
	global_load_lds_dwordx4 v[192:193], off
	ds_read_b128 v[160:163], v199
	ds_read_b128 v[180:183], v199 offset:1024
	ds_read_b128 v[184:187], v199 offset:2048
	ds_read_b128 v[188:191], v199 offset:3072
	ds_read_b128 v[200:203], v199 offset:4096
	ds_read_b128 v[204:207], v199 offset:5120
	ds_read_b128 v[208:211], v199 offset:6144
	ds_read_b128 v[212:215], v199 offset:7168
	s_waitcnt vmcnt(8)
	s_waitcnt lgkmcnt(0)
	s_setprio 1
	s_barrier
	v_mfma_f32_16x16x32_bf16 v[124:127], v[128:131], v[160:163], v[124:127]
	v_mfma_f32_16x16x32_bf16 v[120:123], v[136:139], v[160:163], v[120:123]
	v_mfma_f32_16x16x32_bf16 v[112:115], v[128:131], v[184:187], v[112:115]
	v_mfma_f32_16x16x32_bf16 v[104:107], v[136:139], v[184:187], v[104:107]
	v_mfma_f32_16x16x32_bf16 v[96:99], v[128:131], v[200:203], v[96:99]
	v_mfma_f32_16x16x32_bf16 v[88:91], v[136:139], v[200:203], v[88:91]
	v_mfma_f32_16x16x32_bf16 v[80:83], v[128:131], v[208:211], v[80:83]
	v_mfma_f32_16x16x32_bf16 v[72:75], v[136:139], v[208:211], v[72:75]
	v_mfma_f32_16x16x32_bf16 v[124:127], v[132:135], v[180:183], v[124:127]
	v_mfma_f32_16x16x32_bf16 v[120:123], v[140:143], v[180:183], v[120:123]
	v_mfma_f32_16x16x32_bf16 v[112:115], v[132:135], v[188:191], v[112:115]
	v_mfma_f32_16x16x32_bf16 v[104:107], v[140:143], v[188:191], v[104:107]
	v_mfma_f32_16x16x32_bf16 v[96:99], v[132:135], v[204:207], v[96:99]
	v_mfma_f32_16x16x32_bf16 v[88:91], v[140:143], v[204:207], v[88:91]
	v_mfma_f32_16x16x32_bf16 v[80:83], v[132:135], v[212:215], v[80:83]
	v_mfma_f32_16x16x32_bf16 v[72:75], v[140:143], v[212:215], v[72:75]
	s_setprio 0
	s_setprio 1
	v_mfma_f32_16x16x32_bf16 v[116:119], v[144:147], v[160:163], v[116:119]
	v_mfma_f32_16x16x32_bf16 v[108:111], v[152:155], v[160:163], v[108:111]
	v_mfma_f32_16x16x32_bf16 v[100:103], v[144:147], v[184:187], v[100:103]
	v_mfma_f32_16x16x32_bf16 v[92:95], v[152:155], v[184:187], v[92:95]
	v_mfma_f32_16x16x32_bf16 v[84:87], v[144:147], v[200:203], v[84:87]
	v_mfma_f32_16x16x32_bf16 v[76:79], v[152:155], v[200:203], v[76:79]
	v_mfma_f32_16x16x32_bf16 v[68:71], v[144:147], v[208:211], v[68:71]
	v_mfma_f32_16x16x32_bf16 v[64:67], v[152:155], v[208:211], v[64:67]
	v_mfma_f32_16x16x32_bf16 v[116:119], v[148:151], v[180:183], v[116:119]
	v_mfma_f32_16x16x32_bf16 v[108:111], v[156:159], v[180:183], v[108:111]
	v_mfma_f32_16x16x32_bf16 v[100:103], v[148:151], v[188:191], v[100:103]
	v_mfma_f32_16x16x32_bf16 v[92:95], v[156:159], v[188:191], v[92:95]
	v_mfma_f32_16x16x32_bf16 v[84:87], v[148:151], v[204:207], v[84:87]
	v_mfma_f32_16x16x32_bf16 v[76:79], v[156:159], v[204:207], v[76:79]
	v_mfma_f32_16x16x32_bf16 v[68:71], v[148:151], v[212:215], v[68:71]
	v_mfma_f32_16x16x32_bf16 v[64:67], v[156:159], v[212:215], v[64:67]
	s_barrier
	s_setprio 0
	s_add_i32 s16, s38, s25
	v_lshl_add_u64 v[192:193], s[20:21], 0, v[166:167]
	s_mov_b32 m0, s16
	s_nop 0
	global_load_lds_dwordx4 v[192:193], off
	ds_read_b128 v[160:163], v199 offset:16384
	ds_read_b128 v[180:183], v199 offset:17408
	s_add_i32 m0, s16, 0x2000
	s_add_u32 s16, s20, 0xb0000
	v_lshl_add_u64 v[216:217], s[20:21], 0, v[170:171]
	s_addc_u32 s17, s21, 0
	s_add_i32 s47, s39, s25
	global_load_lds_dwordx4 v[216:217], off
	ds_read_b128 v[184:187], v199 offset:18432
	ds_read_b128 v[188:191], v199 offset:19456
	v_lshl_add_u64 v[218:219], s[16:17], 0, v[166:167]
	s_mov_b32 m0, s47
	v_lshl_add_u64 v[220:221], s[22:23], 0, v[168:169]
	global_load_lds_dwordx4 v[218:219], off
	ds_read_b128 v[200:203], v199 offset:20480
	ds_read_b128 v[204:207], v199 offset:21504
	v_lshl_add_u64 v[218:219], s[16:17], 0, v[170:171]
	s_add_i32 m0, s47, 0x2000
	s_nop 0
	global_load_lds_dwordx4 v[218:219], off
	ds_read_b128 v[208:211], v199 offset:22528
	ds_read_b128 v[212:215], v199 offset:23552
	v_lshl_add_u64 v[218:219], s[22:23], 0, v[164:165]
	s_mov_b32 m0, s26
	s_nop 0
	global_load_lds_dwordx4 v[218:219], off
	s_mov_b32 m0, s27
	s_nop 0
	global_load_lds_dwordx4 v[220:221], off
	s_waitcnt vmcnt(8)
	s_waitcnt lgkmcnt(0)
	s_setprio 1
	s_barrier
	v_mfma_f32_16x16x32_bf16 v[60:63], v[128:131], v[160:163], v[60:63]
	v_mfma_f32_16x16x32_bf16 v[56:59], v[136:139], v[160:163], v[56:59]
	v_mfma_f32_16x16x32_bf16 v[48:51], v[128:131], v[184:187], v[48:51]
	v_mfma_f32_16x16x32_bf16 v[40:43], v[136:139], v[184:187], v[40:43]
	v_mfma_f32_16x16x32_bf16 v[32:35], v[128:131], v[200:203], v[32:35]
	v_mfma_f32_16x16x32_bf16 v[24:27], v[136:139], v[200:203], v[24:27]
	v_mfma_f32_16x16x32_bf16 v[16:19], v[128:131], v[208:211], v[16:19]
	v_mfma_f32_16x16x32_bf16 v[8:11], v[136:139], v[208:211], v[8:11]
	v_mfma_f32_16x16x32_bf16 v[60:63], v[132:135], v[180:183], v[60:63]
	v_mfma_f32_16x16x32_bf16 v[56:59], v[140:143], v[180:183], v[56:59]
	v_mfma_f32_16x16x32_bf16 v[48:51], v[132:135], v[188:191], v[48:51]
	v_mfma_f32_16x16x32_bf16 v[40:43], v[140:143], v[188:191], v[40:43]
	v_mfma_f32_16x16x32_bf16 v[32:35], v[132:135], v[204:207], v[32:35]
	v_mfma_f32_16x16x32_bf16 v[24:27], v[140:143], v[204:207], v[24:27]
	v_mfma_f32_16x16x32_bf16 v[16:19], v[132:135], v[212:215], v[16:19]
	v_mfma_f32_16x16x32_bf16 v[8:11], v[140:143], v[212:215], v[8:11]
	s_setprio 0
	s_setprio 1
	v_mfma_f32_16x16x32_bf16 v[52:55], v[144:147], v[160:163], v[52:55]
	v_mfma_f32_16x16x32_bf16 v[44:47], v[152:155], v[160:163], v[44:47]
	v_mfma_f32_16x16x32_bf16 v[36:39], v[144:147], v[184:187], v[36:39]
	v_mfma_f32_16x16x32_bf16 v[28:31], v[152:155], v[184:187], v[28:31]
	v_mfma_f32_16x16x32_bf16 v[20:23], v[144:147], v[200:203], v[20:23]
	v_mfma_f32_16x16x32_bf16 v[12:15], v[152:155], v[200:203], v[12:15]
	v_mfma_f32_16x16x32_bf16 v[4:7], v[144:147], v[208:211], v[4:7]
	v_mfma_f32_16x16x32_bf16 v[0:3], v[152:155], v[208:211], v[0:3]
	v_mfma_f32_16x16x32_bf16 v[52:55], v[148:151], v[180:183], v[52:55]
	v_mfma_f32_16x16x32_bf16 v[44:47], v[156:159], v[180:183], v[44:47]
	v_mfma_f32_16x16x32_bf16 v[36:39], v[148:151], v[188:191], v[36:39]
	v_mfma_f32_16x16x32_bf16 v[28:31], v[156:159], v[188:191], v[28:31]
	v_mfma_f32_16x16x32_bf16 v[20:23], v[148:151], v[204:207], v[20:23]
	v_mfma_f32_16x16x32_bf16 v[12:15], v[156:159], v[204:207], v[12:15]
	v_mfma_f32_16x16x32_bf16 v[4:7], v[148:151], v[212:215], v[4:7]
	v_mfma_f32_16x16x32_bf16 v[0:3], v[156:159], v[212:215], v[0:3]
	s_barrier
	s_setprio 0
	s_add_i32 s47, 0, 0x18000
	s_add_i32 s48, 0, 0x1c000
	s_add_u32 s16, s22, 0xb0000
	s_addc_u32 s17, s23, 0
	s_mov_b32 m0, s28
	v_lshl_add_u64 v[222:223], s[16:17], 0, v[164:165]
	global_load_lds_dwordx4 v[222:223], off
	v_add_u32_e32 v140, s47, v196
	v_add_u32_e32 v156, s48, v196
	ds_read_b128 v[128:131], v140
	ds_read_b128 v[132:135], v140 offset:1024
	ds_read_b128 v[136:139], v140 offset:2048
	ds_read_b128 v[140:143], v140 offset:3072
	ds_read_b128 v[144:147], v156
	ds_read_b128 v[148:151], v156 offset:1024
	ds_read_b128 v[152:155], v156 offset:2048
	ds_read_b128 v[156:159], v156 offset:3072
	v_lshl_add_u64 v[222:223], s[16:17], 0, v[168:169]
	s_mov_b32 m0, s29
	s_nop 0
	global_load_lds_dwordx4 v[222:223], off
	ds_read_b128 v[160:163], v199 offset:32768
	ds_read_b128 v[180:183], v199 offset:33792
	ds_read_b128 v[184:187], v199 offset:34816
	ds_read_b128 v[188:191], v199 offset:35840
	ds_read_b128 v[200:203], v199 offset:36864
	ds_read_b128 v[204:207], v199 offset:37888
	ds_read_b128 v[208:211], v199 offset:38912
	ds_read_b128 v[212:215], v199 offset:39936
	s_waitcnt vmcnt(8)
	s_waitcnt lgkmcnt(0)
	s_setprio 1
	s_barrier
	v_mfma_f32_16x16x32_bf16 v[124:127], v[128:131], v[160:163], v[124:127]
	v_mfma_f32_16x16x32_bf16 v[120:123], v[136:139], v[160:163], v[120:123]
	v_mfma_f32_16x16x32_bf16 v[112:115], v[128:131], v[184:187], v[112:115]
	v_mfma_f32_16x16x32_bf16 v[104:107], v[136:139], v[184:187], v[104:107]
	v_mfma_f32_16x16x32_bf16 v[96:99], v[128:131], v[200:203], v[96:99]
	v_mfma_f32_16x16x32_bf16 v[88:91], v[136:139], v[200:203], v[88:91]
	v_mfma_f32_16x16x32_bf16 v[80:83], v[128:131], v[208:211], v[80:83]
	v_mfma_f32_16x16x32_bf16 v[72:75], v[136:139], v[208:211], v[72:75]
	v_mfma_f32_16x16x32_bf16 v[124:127], v[132:135], v[180:183], v[124:127]
	v_mfma_f32_16x16x32_bf16 v[120:123], v[140:143], v[180:183], v[120:123]
	v_mfma_f32_16x16x32_bf16 v[112:115], v[132:135], v[188:191], v[112:115]
	v_mfma_f32_16x16x32_bf16 v[104:107], v[140:143], v[188:191], v[104:107]
	v_mfma_f32_16x16x32_bf16 v[96:99], v[132:135], v[204:207], v[96:99]
	v_mfma_f32_16x16x32_bf16 v[88:91], v[140:143], v[204:207], v[88:91]
	v_mfma_f32_16x16x32_bf16 v[80:83], v[132:135], v[212:215], v[80:83]
	v_mfma_f32_16x16x32_bf16 v[72:75], v[140:143], v[212:215], v[72:75]
	s_setprio 0
	s_setprio 1
	v_mfma_f32_16x16x32_bf16 v[116:119], v[144:147], v[160:163], v[116:119]
	v_mfma_f32_16x16x32_bf16 v[108:111], v[152:155], v[160:163], v[108:111]
	v_mfma_f32_16x16x32_bf16 v[100:103], v[144:147], v[184:187], v[100:103]
	v_mfma_f32_16x16x32_bf16 v[92:95], v[152:155], v[184:187], v[92:95]
	v_mfma_f32_16x16x32_bf16 v[84:87], v[144:147], v[200:203], v[84:87]
	v_mfma_f32_16x16x32_bf16 v[76:79], v[152:155], v[200:203], v[76:79]
	v_mfma_f32_16x16x32_bf16 v[68:71], v[144:147], v[208:211], v[68:71]
	v_mfma_f32_16x16x32_bf16 v[64:67], v[152:155], v[208:211], v[64:67]
	v_mfma_f32_16x16x32_bf16 v[116:119], v[148:151], v[180:183], v[116:119]
	v_mfma_f32_16x16x32_bf16 v[108:111], v[156:159], v[180:183], v[108:111]
	v_mfma_f32_16x16x32_bf16 v[100:103], v[148:151], v[188:191], v[100:103]
	v_mfma_f32_16x16x32_bf16 v[92:95], v[156:159], v[188:191], v[92:95]
	v_mfma_f32_16x16x32_bf16 v[84:87], v[148:151], v[204:207], v[84:87]
	v_mfma_f32_16x16x32_bf16 v[76:79], v[156:159], v[204:207], v[76:79]
	v_mfma_f32_16x16x32_bf16 v[68:71], v[148:151], v[212:215], v[68:71]
	v_mfma_f32_16x16x32_bf16 v[64:67], v[156:159], v[212:215], v[64:67]
	s_barrier
	s_setprio 0
	s_add_i32 s16, s47, s25
	v_lshl_add_u64 v[192:193], v[192:193], 0, s[10:11]
	s_mov_b32 m0, s16
	s_nop 0
	global_load_lds_dwordx4 v[192:193], off
	ds_read_b128 v[160:163], v199 offset:49152
	ds_read_b128 v[180:183], v199 offset:50176
	s_add_i32 m0, s16, 0x2000
	s_add_u32 s16, s20, 0xb0080
	v_lshl_add_u64 v[192:193], v[216:217], 0, s[10:11]
	s_addc_u32 s17, s21, 0
	s_add_i32 s20, s48, s25
	global_load_lds_dwordx4 v[192:193], off
	ds_read_b128 v[184:187], v199 offset:51200
	ds_read_b128 v[188:191], v199 offset:52224
	v_lshl_add_u64 v[192:193], s[16:17], 0, v[166:167]
	s_mov_b32 m0, s20
	s_nop 0
	global_load_lds_dwordx4 v[192:193], off
	ds_read_b128 v[200:203], v199 offset:53248
	ds_read_b128 v[204:207], v199 offset:54272
	v_lshl_add_u64 v[192:193], s[16:17], 0, v[170:171]
	s_add_i32 m0, s20, 0x2000
	s_nop 0
	global_load_lds_dwordx4 v[192:193], off
	ds_read_b128 v[208:211], v199 offset:55296
	ds_read_b128 v[212:215], v199 offset:56320
	v_lshl_add_u64 v[192:193], v[218:219], 0, s[10:11]
	s_mov_b32 m0, s35
	s_nop 0
	global_load_lds_dwordx4 v[192:193], off
	v_lshl_add_u64 v[192:193], v[220:221], 0, s[10:11]
	s_mov_b32 m0, s36
	s_nop 0
	global_load_lds_dwordx4 v[192:193], off
	s_waitcnt vmcnt(8)
	s_waitcnt lgkmcnt(0)
	s_setprio 1
	s_barrier
	v_mfma_f32_16x16x32_bf16 v[60:63], v[128:131], v[160:163], v[60:63]
	v_mfma_f32_16x16x32_bf16 v[56:59], v[136:139], v[160:163], v[56:59]
	v_mfma_f32_16x16x32_bf16 v[48:51], v[128:131], v[184:187], v[48:51]
	v_mfma_f32_16x16x32_bf16 v[40:43], v[136:139], v[184:187], v[40:43]
	v_mfma_f32_16x16x32_bf16 v[32:35], v[128:131], v[200:203], v[32:35]
	v_mfma_f32_16x16x32_bf16 v[24:27], v[136:139], v[200:203], v[24:27]
	v_mfma_f32_16x16x32_bf16 v[16:19], v[128:131], v[208:211], v[16:19]
	v_mfma_f32_16x16x32_bf16 v[8:11], v[136:139], v[208:211], v[8:11]
	v_mfma_f32_16x16x32_bf16 v[60:63], v[132:135], v[180:183], v[60:63]
	v_mfma_f32_16x16x32_bf16 v[56:59], v[140:143], v[180:183], v[56:59]
	v_mfma_f32_16x16x32_bf16 v[48:51], v[132:135], v[188:191], v[48:51]
	v_mfma_f32_16x16x32_bf16 v[40:43], v[140:143], v[188:191], v[40:43]
	v_mfma_f32_16x16x32_bf16 v[32:35], v[132:135], v[204:207], v[32:35]
	v_mfma_f32_16x16x32_bf16 v[24:27], v[140:143], v[204:207], v[24:27]
	v_mfma_f32_16x16x32_bf16 v[16:19], v[132:135], v[212:215], v[16:19]
	v_mfma_f32_16x16x32_bf16 v[8:11], v[140:143], v[212:215], v[8:11]
	s_setprio 0
	s_setprio 1
	v_mfma_f32_16x16x32_bf16 v[52:55], v[144:147], v[160:163], v[52:55]
	v_mfma_f32_16x16x32_bf16 v[44:47], v[152:155], v[160:163], v[44:47]
	v_mfma_f32_16x16x32_bf16 v[36:39], v[144:147], v[184:187], v[36:39]
	v_mfma_f32_16x16x32_bf16 v[28:31], v[152:155], v[184:187], v[28:31]
	v_mfma_f32_16x16x32_bf16 v[20:23], v[144:147], v[200:203], v[20:23]
	v_mfma_f32_16x16x32_bf16 v[12:15], v[152:155], v[200:203], v[12:15]
	v_mfma_f32_16x16x32_bf16 v[4:7], v[144:147], v[208:211], v[4:7]
	v_mfma_f32_16x16x32_bf16 v[0:3], v[152:155], v[208:211], v[0:3]
	v_mfma_f32_16x16x32_bf16 v[52:55], v[148:151], v[180:183], v[52:55]
	v_mfma_f32_16x16x32_bf16 v[44:47], v[156:159], v[180:183], v[44:47]
	v_mfma_f32_16x16x32_bf16 v[36:39], v[148:151], v[188:191], v[36:39]
	v_mfma_f32_16x16x32_bf16 v[28:31], v[156:159], v[188:191], v[28:31]
	v_mfma_f32_16x16x32_bf16 v[20:23], v[148:151], v[204:207], v[20:23]
	v_mfma_f32_16x16x32_bf16 v[12:15], v[156:159], v[204:207], v[12:15]
	v_mfma_f32_16x16x32_bf16 v[4:7], v[148:151], v[212:215], v[4:7]
	v_mfma_f32_16x16x32_bf16 v[0:3], v[156:159], v[212:215], v[0:3]
	s_barrier
	s_setprio 0
	s_add_i32 s46, s46, 2
	s_add_u32 s44, s44, 0x100
	s_addc_u32 s45, s45, 0
	s_cmp_gt_u32 s46, 41
	s_mov_b64 s[16:17], s[18:19]
	s_cbranch_scc0 .LBB0_1273
	s_and_b64 vcc, exec, s[12:13]
	s_cbranch_vccz .LBB0_1276
	s_barrier
